# adds: P4 MIX stores widened to 16-byte write-through (lane^16 exchange via v_permlane16_swap) so grid seam 4 has no dirty L2 to write back
# baseline (speedup 1.0000x reference)
; #define LAS __attribute__((address_space(3)))
; __device__ __forceinline__ float log_sigmoid(float x) { return -log1pf(expf(-x)); }
; __device__ __forceinline__ void ret_unit(LAS unsigned char* lds, int u, const bf16* PROJ, const int* pos, const float* dec_f, const float* dec_b, const bf16* ST,
;                                          const float* gn_w, const float* gn_b, bf16* MIX, int tid, const WsRef& wsr) {
;     ...
;     const int bh = u >> 6, c = u & 63, b = bh >> 2, h = bh & 3;
;     const size_t row0 = (size_t)b * SEQ + (size_t)c * 128;
;     LAS bf16* Qs = (LAS bf16*)lds; LAS bf16* Ks = (LAS bf16*)(lds + TILE_B); LAS bf16* VT = (LAS bf16*)(lds + 2 * TILE_B);
;     const float lgf2 = log_sigmoid(dec_f[h]) * LOG2E, lgb2 = log_sigmoid(dec_b[h]) * LOG2E;
.LBB0_438:
	s_ashr_i32 s0, s73, 6
	s_and_b32 s80, s0, 3
	s_lshl_b32 s1, s80, 2
	v_mov_b32_e32 v16, s1
	global_load_dword v0, v16, s[18:19]
	s_mov_b32 s1, 0x42ce8ed0
	s_mov_b32 s83, 0xc2b17218
	s_mov_b32 s11, 0x3f2aaaab
	s_mov_b32 s88, 0x7f800000
	s_mov_b32 s8, 0x33800000
	s_and_b32 s82, s73, 63
	s_ashr_i32 s4, s73, 8
	s_ashr_i32 s5, s4, 31
	s_lshl_b32 s81, s82, 7
	s_waitcnt vmcnt(0)
	v_mul_f32_e32 v1, 0xbfb8aa3b, v0
	v_fma_f32 v2, v0, s41, -v1
	v_rndne_f32_e32 v3, v1
	v_fmac_f32_e32 v2, 0xb2a5705f, v0
	v_sub_f32_e32 v1, v1, v3
	v_add_f32_e32 v1, v1, v2
	v_exp_f32_e32 v1, v1
	v_cvt_i32_f32_e32 v2, v3
	v_cmp_nlt_f32_e64 s[68:69], s1, v0
	v_ldexp_f32 v1, v1, v2
	s_nop 0
	v_cndmask_b32_e64 v1, 0, v1, s[68:69]
	v_cmp_ngt_f32_e64 s[68:69], s83, v0
	s_nop 1
	v_cndmask_b32_e64 v17, v228, v1, s[68:69]
	v_add_f32_e32 v2, 1.0, v17
	v_add_f32_e32 v0, -1.0, v2
	v_sub_f32_e32 v1, v0, v2
	v_add_f32_e32 v1, 1.0, v1
	v_sub_f32_e32 v0, v17, v0
	v_add_f32_e32 v3, v0, v1
	v_frexp_mant_f32_e32 v0, v2
	v_cmp_gt_f32_e64 s[68:69], s11, v0
	v_cvt_f64_f32_e32 v[0:1], v2
	v_frexp_exp_i32_f64_e32 v0, v[0:1]
	v_subbrev_co_u32_e64 v8, s[68:69], 0, v0, s[68:69]
	v_sub_u32_e32 v0, 0, v8
	v_ldexp_f32 v1, v2, v0
	v_add_f32_e32 v2, -1.0, v1
	v_add_f32_e32 v4, 1.0, v1
	v_ldexp_f32 v0, v3, v0
	v_add_f32_e32 v3, 1.0, v2
	v_add_f32_e32 v5, -1.0, v4
	v_sub_f32_e32 v3, v1, v3
	v_sub_f32_e32 v1, v1, v5
	v_add_f32_e32 v3, v0, v3
	v_add_f32_e32 v0, v0, v1
	v_add_f32_e32 v9, v4, v0
	v_rcp_f32_e32 v11, v9
	v_sub_f32_e32 v1, v4, v9
	v_add_f32_e32 v10, v0, v1
	v_add_f32_e32 v1, v2, v3
	v_mul_f32_e32 v13, v1, v11
	v_sub_f32_e32 v0, v2, v1
	v_mul_f32_e32 v2, v9, v13
	v_fma_f32 v4, v13, v9, -v2
	v_fmac_f32_e32 v4, v13, v10
	v_add_f32_e32 v12, v3, v0
	v_add_f32_e32 v0, v2, v4
	v_sub_f32_e32 v3, v1, v0
	v_pk_add_f32 v[6:7], v[0:1], v[2:3] neg_lo:[0,1] neg_hi:[0,1]
	v_mov_b32_e32 v5, v0
	v_pk_add_f32 v[0:1], v[6:7], v[4:5] neg_lo:[0,1] neg_hi:[0,1]
	v_cmp_neq_f32_e64 s[68:69], s88, v17
	v_add_f32_e32 v1, v12, v1
	v_add_f32_e32 v0, v0, v1
	v_add_f32_e32 v1, v3, v0
	v_mul_f32_e32 v12, v11, v1
	v_mul_f32_e32 v2, v9, v12
	v_fma_f32 v4, v12, v9, -v2
	v_fmac_f32_e32 v4, v12, v10
	v_sub_f32_e32 v3, v3, v1
	v_add_f32_e32 v9, v0, v3
	v_add_f32_e32 v0, v2, v4
	v_sub_f32_e32 v3, v1, v0
	v_pk_add_f32 v[6:7], v[0:1], v[2:3] neg_lo:[0,1] neg_hi:[0,1]
	v_mov_b32_e32 v5, v0
	v_pk_add_f32 v[0:1], v[6:7], v[4:5] neg_lo:[0,1] neg_hi:[0,1]
	s_nop 0
	v_add_f32_e32 v1, v9, v1
	v_add_f32_e32 v0, v0, v1
	v_add_f32_e32 v1, v13, v12
	v_add_f32_e32 v0, v3, v0
	v_sub_f32_e32 v2, v1, v13
	v_mul_f32_e32 v0, v11, v0
	v_sub_f32_e32 v2, v12, v2
	v_add_f32_e32 v2, v2, v0
	v_add_f32_e32 v4, v1, v2
	v_mul_f32_e32 v5, v4, v4
	v_fmamk_f32 v0, v5, 0x3e9b6dac, v223
	v_fmaak_f32 v105, v5, v0, 0x3f2aaada
	v_cvt_f32_i32_e32 v0, v8
	v_sub_f32_e32 v1, v4, v1
	v_sub_f32_e32 v1, v2, v1
	v_ldexp_f32 v6, v1, 1
	v_mul_f32_e32 v1, v4, v5
	v_ldexp_f32 v3, v4, 1
	v_pk_mul_f32 v[4:5], v[0:1], v[104:105]
	s_nop 0
	v_fma_f32 v2, v0, s33, -v4
	v_fmac_f32_e32 v2, 0xb102e308, v0
	v_pk_add_f32 v[0:1], v[4:5], v[2:3]
	s_nop 0
	v_sub_f32_e32 v3, v1, v3
	v_sub_f32_e32 v3, v5, v3
	v_add_f32_e32 v7, v6, v3
	v_mov_b32_e32 v6, v4
	v_pk_add_f32 v[4:5], v[0:1], v[4:5] neg_lo:[0,1] neg_hi:[0,1]
	v_pk_add_f32 v[8:9], v[0:1], v[6:7]
	v_mov_b32_e32 v3, v0
	v_mov_b32_e32 v5, v9
	v_pk_add_f32 v[10:11], v[2:3], v[4:5] neg_lo:[0,1] neg_hi:[0,1]
	v_pk_add_f32 v[2:3], v[2:3], v[4:5]
	v_mov_b32_e32 v14, v1
	v_pk_add_f32 v[4:5], v[2:3], v[0:1] op_sel:[1,0] op_sel_hi:[0,1] neg_lo:[0,1] neg_hi:[0,1]
	v_pk_add_f32 v[12:13], v[8:9], v[4:5] op_sel_hi:[1,0] neg_lo:[0,1] neg_hi:[0,1]
	v_mov_b32_e32 v8, v9
	v_mov_b32_e32 v9, v3
	v_mov_b32_e32 v15, v4
	v_pk_add_f32 v[4:5], v[8:9], v[14:15] neg_lo:[0,1] neg_hi:[0,1]
	v_mov_b32_e32 v6, v7
	v_mov_b32_e32 v7, v0
	v_pk_add_f32 v[0:1], v[6:7], v[4:5] neg_lo:[0,1] neg_hi:[0,1]
	v_mov_b32_e32 v12, v10
	v_pk_add_f32 v[4:5], v[12:13], v[0:1]
	v_mov_b32_e32 v11, v3
	v_pk_add_f32 v[6:7], v[4:5], v[4:5] op_sel:[0,1] op_sel_hi:[1,0]
	s_nop 0
	v_pk_add_f32 v[2:3], v[2:3], v[6:7] op_sel:[1,0] op_sel_hi:[0,1]
	v_mov_b32_e32 v5, v2
	v_pk_add_f32 v[8:9], v[4:5], v[10:11] neg_lo:[0,1] neg_hi:[0,1]
	v_mov_b32_e32 v1, v6
	v_sub_f32_e32 v3, v4, v8
	v_pk_add_f32 v[0:1], v[0:1], v[8:9] neg_lo:[0,1] neg_hi:[0,1]
	v_sub_f32_e32 v3, v10, v3
	v_add_f32_e32 v0, v0, v3
	v_add_f32_e32 v0, v0, v1
	global_load_dword v1, v16, s[20:21]
	v_add_f32_e32 v0, v2, v0
	v_cndmask_b32_e64 v0, v228, v0, s[68:69]
	v_cmp_lt_f32_e64 s[68:69], |v17|, s8
	s_waitcnt vmcnt(0)
; __device__ __forceinline__ u32x4 ws_load16(const WsRef& w, unsigned byte_off) { return __builtin_bit_cast(u32x4, __builtin_amdgcn_raw_buffer_load_b128(w.r, byte_off, 0, 0)); }
; __device__ __forceinline__ float log_sigmoid(float x) { return -log1pf(expf(-x)); }
; __device__ __forceinline__ void ret_unit(LAS unsigned char* lds, int u, const bf16* PROJ, const int* pos, const float* dec_f, const float* dec_b, const bf16* ST,
;                                          const float* gn_w, const float* gn_b, bf16* MIX, int tid, const WsRef& wsr) {
;     ...
;     const float lgf2 = log_sigmoid(dec_f[h]) * LOG2E, lgb2 = log_sigmoid(dec_b[h]) * LOG2E;
;     const u32x4* sfp = (const u32x4*)(ST + ((size_t)bh * 64 + c) * 16384); const u32x4* sbp = (const u32x4*)(ST + ((size_t)(8 + bh) * 64 + c) * 16384);
;     u32x4 sf[4], sb[4];
; #pragma unroll
;     for (int i = 0; i < 4; ++i) { sf[i] = sfp[tid + 512 * i]; sb[i] = sbp[tid + 512 * i]; }
;     u32x4 rq1[2], rq2[2], rk1[2], rk2[2], rv[4]; float rp[2];
; #pragma unroll
;     for (int ii = 0; ii < 2; ++ii) { const int it = tid + 512 * ii, dc = it & 7, j = it >> 3; const unsigned qo = (unsigned)WS_PROJ + (unsigned)(((unsigned)(row0 + j) * INC + h * 128 + dc * 8) * 2u);
;         rq1[ii] = ws_load16(wsr, qo); rq2[ii] = ws_load16(wsr, qo + 128u); rk1[ii] = ws_load16(wsr, qo + 1024u); rk2[ii] = ws_load16(wsr, qo + 1152u); rp[ii] = (float)pos[row0 + j]; }
	v_mul_f32_e32 v2, 0xbfb8aa3b, v1
	v_fma_f32 v3, v1, s41, -v2
	v_rndne_f32_e32 v4, v2
	v_fmac_f32_e32 v3, 0xb2a5705f, v1
	v_sub_f32_e32 v2, v2, v4
	v_add_f32_e32 v2, v2, v3
	v_exp_f32_e32 v2, v2
	v_cvt_i32_f32_e32 v3, v4
	v_cndmask_b32_e64 v0, v0, v17, s[68:69]
	v_cmp_nlt_f32_e64 s[68:69], s1, v1
	s_ashr_i32 s1, s0, 31
	v_ldexp_f32 v2, v2, v3
	v_cndmask_b32_e64 v2, 0, v2, s[68:69]
	v_cmp_ngt_f32_e64 s[68:69], s83, v1
	s_lshl_b64 s[0:1], s[0:1], 21
	s_add_u32 s0, s54, s0
	v_cndmask_b32_e64 v1, v228, v2, s[68:69]
	v_add_f32_e32 v4, 1.0, v1
	v_add_f32_e32 v2, -1.0, v4
	v_sub_f32_e32 v3, v2, v4
	v_add_f32_e32 v3, 1.0, v3
	v_sub_f32_e32 v2, v1, v2
	v_add_f32_e32 v5, v2, v3
	v_frexp_mant_f32_e32 v2, v4
	v_cmp_gt_f32_e64 s[68:69], s11, v2
	v_cvt_f64_f32_e32 v[2:3], v4
	v_frexp_exp_i32_f64_e32 v2, v[2:3]
	v_subbrev_co_u32_e64 v10, s[68:69], 0, v2, s[68:69]
	v_sub_u32_e32 v2, 0, v10
	v_ldexp_f32 v3, v4, v2
	v_add_f32_e32 v4, -1.0, v3
	v_add_f32_e32 v6, 1.0, v3
	v_ldexp_f32 v2, v5, v2
	v_add_f32_e32 v5, 1.0, v4
	v_add_f32_e32 v7, -1.0, v6
	v_sub_f32_e32 v5, v3, v5
	v_sub_f32_e32 v3, v3, v7
	v_add_f32_e32 v5, v2, v5
	v_add_f32_e32 v2, v2, v3
	v_add_f32_e32 v11, v6, v2
	v_rcp_f32_e32 v13, v11
	v_sub_f32_e32 v3, v6, v11
	v_add_f32_e32 v12, v2, v3
	v_add_f32_e32 v3, v4, v5
	v_mul_f32_e32 v15, v3, v13
	v_sub_f32_e32 v2, v4, v3
	v_mul_f32_e32 v4, v11, v15
	v_fma_f32 v6, v15, v11, -v4
	v_fmac_f32_e32 v6, v15, v12
	v_add_f32_e32 v14, v5, v2
	v_add_f32_e32 v2, v4, v6
	v_sub_f32_e32 v5, v3, v2
	v_pk_add_f32 v[8:9], v[2:3], v[4:5] neg_lo:[0,1] neg_hi:[0,1]
	v_mov_b32_e32 v7, v2
	v_pk_add_f32 v[2:3], v[8:9], v[6:7] neg_lo:[0,1] neg_hi:[0,1]
	v_cmp_neq_f32_e64 s[68:69], s88, v1
	v_add_f32_e32 v3, v14, v3
	v_add_f32_e32 v2, v2, v3
	v_add_f32_e32 v3, v5, v2
	v_mul_f32_e32 v14, v13, v3
	v_mul_f32_e32 v4, v11, v14
	v_fma_f32 v6, v14, v11, -v4
	v_fmac_f32_e32 v6, v14, v12
	v_sub_f32_e32 v5, v5, v3
	v_add_f32_e32 v11, v2, v5
	v_add_f32_e32 v2, v4, v6
	v_sub_f32_e32 v5, v3, v2
	v_pk_add_f32 v[8:9], v[2:3], v[4:5] neg_lo:[0,1] neg_hi:[0,1]
	v_mov_b32_e32 v7, v2
	v_pk_add_f32 v[2:3], v[8:9], v[6:7] neg_lo:[0,1] neg_hi:[0,1]
	s_addc_u32 s1, s55, s1
	v_add_f32_e32 v3, v11, v3
	v_add_f32_e32 v2, v2, v3
	v_add_f32_e32 v3, v15, v14
	v_add_f32_e32 v2, v5, v2
	v_sub_f32_e32 v4, v3, v15
	v_mul_f32_e32 v2, v13, v2
	v_sub_f32_e32 v4, v14, v4
	v_add_f32_e32 v4, v4, v2
	v_add_f32_e32 v6, v3, v4
	v_mul_f32_e32 v7, v6, v6
	v_fmamk_f32 v2, v7, 0x3e9b6dac, v223
	v_fmaak_f32 v105, v7, v2, 0x3f2aaada
	v_cvt_f32_i32_e32 v2, v10
	v_sub_f32_e32 v3, v6, v3
	v_sub_f32_e32 v3, v4, v3
	v_ldexp_f32 v8, v3, 1
	v_mul_f32_e32 v3, v6, v7
	v_ldexp_f32 v5, v6, 1
	v_pk_mul_f32 v[6:7], v[2:3], v[104:105]
	v_mul_f32_e32 v105, 0xbfb8aa3b, v0
	v_fma_f32 v4, v2, s33, -v6
	v_fmac_f32_e32 v4, 0xb102e308, v2
	v_pk_add_f32 v[2:3], v[6:7], v[4:5]
	s_mov_b32 s88, s84
	v_sub_f32_e32 v5, v3, v5
	v_sub_f32_e32 v5, v7, v5
	v_add_f32_e32 v9, v8, v5
	v_mov_b32_e32 v8, v6
	v_pk_add_f32 v[6:7], v[2:3], v[6:7] neg_lo:[0,1] neg_hi:[0,1]
	v_pk_add_f32 v[10:11], v[2:3], v[8:9]
	v_mov_b32_e32 v5, v2
	v_mov_b32_e32 v7, v11
	v_pk_add_f32 v[12:13], v[4:5], v[6:7] neg_lo:[0,1] neg_hi:[0,1]
	v_pk_add_f32 v[4:5], v[4:5], v[6:7]
	v_mov_b32_e32 v16, v3
	v_pk_add_f32 v[6:7], v[4:5], v[2:3] op_sel:[1,0] op_sel_hi:[0,1] neg_lo:[0,1] neg_hi:[0,1]
	v_pk_add_f32 v[14:15], v[10:11], v[6:7] op_sel_hi:[1,0] neg_lo:[0,1] neg_hi:[0,1]
	v_mov_b32_e32 v10, v11
	v_mov_b32_e32 v11, v5
	v_mov_b32_e32 v17, v6
	v_pk_add_f32 v[6:7], v[10:11], v[16:17] neg_lo:[0,1] neg_hi:[0,1]
	v_mov_b32_e32 v8, v9
	v_mov_b32_e32 v9, v2
	v_pk_add_f32 v[2:3], v[8:9], v[6:7] neg_lo:[0,1] neg_hi:[0,1]
	v_mov_b32_e32 v14, v12
	v_pk_add_f32 v[6:7], v[14:15], v[2:3]
	v_mov_b32_e32 v13, v5
	v_pk_add_f32 v[8:9], v[6:7], v[6:7] op_sel:[0,1] op_sel_hi:[1,0]
	s_nop 0
	v_pk_add_f32 v[4:5], v[4:5], v[8:9] op_sel:[1,0] op_sel_hi:[0,1]
	v_mov_b32_e32 v7, v4
	v_pk_add_f32 v[10:11], v[6:7], v[12:13] neg_lo:[0,1] neg_hi:[0,1]
	v_mov_b32_e32 v3, v8
	v_sub_f32_e32 v5, v6, v10
	v_pk_add_f32 v[2:3], v[2:3], v[10:11] neg_lo:[0,1] neg_hi:[0,1]
	v_sub_f32_e32 v5, v12, v5
	v_add_f32_e32 v2, v2, v5
	v_add_f32_e32 v2, v2, v3
	v_add_f32_e32 v2, v4, v2
	v_cndmask_b32_e64 v2, v228, v2, s[68:69]
	v_cmp_lt_f32_e64 s[68:69], |v1|, s8
	s_movk_i32 s8, 0x2000
	s_nop 0
	v_cndmask_b32_e64 v48, v2, v1, s[68:69]
	s_lshl_b32 s68, s82, 15
	s_add_u32 s0, s0, s68
	s_addc_u32 s1, s1, 0
	s_add_u32 s82, s0, 0x1000000
	v_lshl_add_u64 v[2:3], s[0:1], 0, v[96:97]
	s_addc_u32 s83, s1, 0
	v_add_co_u32_e64 v8, s[68:69], s8, v2
	v_lshl_add_u64 v[28:29], s[82:83], 0, v[96:97]
	s_nop 0
	v_addc_co_u32_e64 v9, s[68:69], 0, v3, s[68:69]
	v_add_co_u32_e64 v16, s[68:69], s8, v28
	global_load_dwordx4 v[4:7], v96, s[0:1]
	global_load_dwordx4 v[12:15], v96, s[82:83]
	v_addc_co_u32_e64 v17, s[68:69], 0, v29, s[68:69]
	global_load_dwordx4 v[8:11], v[8:9], off
	s_nop 0
	global_load_dwordx4 v[16:19], v[16:17], off
	s_nop 0
	global_load_dwordx4 v[24:27], v224, s[0:1]
	global_load_dwordx4 v[20:23], v224, s[82:83]
	s_movk_i32 s0, 0x6000
	v_add_co_u32_e64 v2, s[68:69], s0, v2
	s_lshl_b64 s[4:5], s[4:5], 13
	s_nop 0
	v_addc_co_u32_e64 v3, s[68:69], 0, v3, s[68:69]
	global_load_dwordx4 v[32:35], v[2:3], off
	v_add_co_u32_e64 v2, s[68:69], s0, v28
	s_or_b32 s4, s4, s81
	s_nop 0
	v_addc_co_u32_e64 v3, s[68:69], 0, v29, s[68:69]
	s_lshl_b32 s0, s80, 7
	v_or_b32_e32 v0, s4, v98
	global_load_dwordx4 v[36:39], v[2:3], off
	v_or_b32_e32 v2, s0, v106
	v_mul_lo_u32 v3, v0, s9
	v_mov_b32_e32 v1, s5
	v_or_b32_e32 v3, v3, v2
	v_lshl_add_u32 v3, v3, 1, v229
	v_lshl_add_u64 v[0:1], v[0:1], 2, s[12:13]
	buffer_load_dwordx4 v[50:53], v3, s[88:91], 0 offen
; __device__ __forceinline__ u32x4 ws_load16(const WsRef& w, unsigned byte_off) { return __builtin_bit_cast(u32x4, __builtin_amdgcn_raw_buffer_load_b128(w.r, byte_off, 0, 0)); }
; __device__ __forceinline__ float fexp2(float x) { return __builtin_amdgcn_exp2f(x); }
; __device__ __forceinline__ void ret_unit(LAS unsigned char* lds, int u, const bf16* PROJ, const int* pos, const float* dec_f, const float* dec_b, const bf16* ST,
;                                          const float* gn_w, const float* gn_b, bf16* MIX, int tid, const WsRef& wsr) {
;     ...
;     for (int ii = 0; ii < 2; ++ii) { const int it = tid + 512 * ii, dc = it & 7, j = it >> 3; const unsigned qo = (unsigned)WS_PROJ + (unsigned)(((unsigned)(row0 + j) * INC + h * 128 + dc * 8) * 2u);
;         rq1[ii] = ws_load16(wsr, qo); rq2[ii] = ws_load16(wsr, qo + 128u); rk1[ii] = ws_load16(wsr, qo + 1024u); rk2[ii] = ws_load16(wsr, qo + 1152u); rp[ii] = (float)pos[row0 + j]; }
; #pragma unroll
;     for (int ii = 0; ii < 2; ++ii) { const int it = tid + 512 * ii, dc = it & 7, j = it >> 3;
;         const u32x4 q1 = rq1[ii], q2 = rq2[ii], k1 = rk1[ii], k2 = rk2[ii];
;         const float p = rp[ii];
;         float sn[8], cs[8];
; #pragma unroll
;         for (int e = 0; e < 8; ++e) { const int i = dc * 8 + e; const float inv = fexp2(-(float)i * 0.20762050593046015f); fast_sincos(p * inv, sn[e], cs[e]); }
;     ...
;         for (int r = 0; r < 4; ++r) { const int key = n * 16 + 4 * fq + r; const int df = q - key; const float f = df >= 0 ? fexp2(lgf2 * (float)df) : fexp2(lgb2 * (float)(-df)); s[n][r] *= f; } }
	buffer_load_dwordx4 v[54:57], v3, s[88:91], 0 offen offset:128
	buffer_load_dwordx4 v[58:61], v3, s[88:91], 0 offen offset:1024
	buffer_load_dwordx4 v[62:65], v3, s[88:91], 0 offen offset:1152
	v_lshl_add_u64 v[66:67], s[4:5], 0, v[100:101]
	global_load_dword v0, v[0:1], off
	v_mul_f32_e32 v230, 0xbfb8aa3b, v48
	v_cndmask_b32_e64 v89, v105, v230, s[30:31]
	v_cndmask_b32_e64 v94, v105, v230, s[56:57]
	v_cndmask_b32_e64 v95, v105, v230, s[58:59]
	v_mul_f32_e32 v89, v89, v137
	v_cndmask_b32_e64 v92, v105, v230, s[74:75]
	v_cndmask_b32_e64 v93, v105, v230, s[76:77]
	v_mul_f32_e32 v94, v94, v142
	v_mul_f32_e32 v95, v95, v143
	v_exp_f32_e32 v89, v89
	v_mul_f32_e32 v92, v92, v140
	v_mul_f32_e32 v93, v93, v141
	v_exp_f32_e32 v94, v94
	v_exp_f32_e32 v95, v95
	v_exp_f32_e32 v92, v92
	v_exp_f32_e32 v93, v93
	v_cndmask_b32_e64 v130, v105, v230, s[60:61]
	v_cndmask_b32_e64 v131, v105, v230, s[62:63]
	v_cndmask_b32_e64 v48, v105, v230, s[42:43]
	v_mul_f32_e32 v130, v130, v144
	v_mul_f32_e32 v131, v131, v145
	v_mul_f32_e32 v48, v48, v127
	v_exp_f32_e32 v130, v130
	v_exp_f32_e32 v131, v131
	v_exp_f32_e32 v48, v48
	v_cndmask_b32_e64 v90, v105, v230, s[34:35]
	v_cndmask_b32_e64 v91, v105, v230, s[38:39]
	v_mul_f32_e32 v90, v90, v138
	v_mul_f32_e32 v91, v91, v139
	v_exp_f32_e32 v90, v90
	v_exp_f32_e32 v91, v91
	v_cndmask_b32_e64 v238, v105, v230, s[94:95]
	v_mul_f32_e32 v238, v238, v154
	v_exp_f32_e32 v238, v238
	v_cndmask_b32_e64 v234, v105, v230, s[78:79]
	v_cndmask_b32_e64 v235, v105, v230, s[2:3]
	v_cndmask_b32_e64 v236, v105, v230, s[92:93]
	v_cndmask_b32_e32 v237, v105, v230, vcc
	v_mul_f32_e32 v234, v234, v150
	v_mul_f32_e32 v235, v235, v151
	v_mul_f32_e32 v236, v236, v152
	v_mul_f32_e32 v237, v237, v153
	v_exp_f32_e32 v234, v234
	v_exp_f32_e32 v235, v235
	v_exp_f32_e32 v236, v236
	v_exp_f32_e32 v237, v237
	v_cndmask_b32_e64 v132, v105, v230, s[64:65]
	v_cndmask_b32_e64 v133, v105, v230, s[14:15]
	v_cndmask_b32_e64 v232, v105, v230, s[16:17]
	v_cndmask_b32_e64 v233, v105, v230, s[24:25]
	v_mul_f32_e32 v132, v132, v146
	v_mul_f32_e32 v133, v133, v147
	v_mul_f32_e32 v232, v232, v148
	v_mul_f32_e32 v233, v233, v149
	v_exp_f32_e32 v132, v132
	v_exp_f32_e32 v133, v133
	v_exp_f32_e32 v232, v232
	v_exp_f32_e32 v233, v233
	s_mov_b32 s1, 0x800000
	s_add_i32 s73, s73, s40
	s_cmpk_lt_i32 s73, 0x200
	s_waitcnt vmcnt(4)
	v_lshlrev_b32_e32 v82, 16, v50
	s_waitcnt vmcnt(3)
	v_lshlrev_b32_e32 v84, 16, v54
	v_and_b32_e32 v85, 0xffff0000, v54
	v_and_b32_e32 v83, 0xffff0000, v50
	s_waitcnt vmcnt(0)
	v_cvt_f32_i32_e32 v49, v0
	v_mul_lo_u32 v0, v66, s9
	v_or_b32_e32 v0, v0, v2
	v_lshl_add_u32 v0, v0, 1, v229
	v_lshl_add_u64 v[66:67], v[66:67], 2, s[12:13]
	buffer_load_dwordx4 v[44:47], v0, s[88:91], 0 offen
	buffer_load_dwordx4 v[40:43], v0, s[88:91], 0 offen offset:128
	buffer_load_dwordx4 v[28:31], v0, s[88:91], 0 offen offset:1024
	s_nop 0
	buffer_load_dwordx4 v[0:3], v0, s[88:91], 0 offen offset:1152
	v_mul_f32_e32 v70, v109, v49
	global_load_dword v66, v[66:67], off
	v_mul_f32_e32 v71, 0.15915494, v70
	v_rndne_f32_e32 v71, v71
	v_fmac_f32_e32 v70, 0xc0c90000, v71
	v_fmac_f32_e32 v70, 0xbafdaa22, v71
	v_mul_f32_e32 v71, 0.15915494, v70
	v_sin_f32_e32 v70, v71
	v_cos_f32_e32 v72, v71
	v_mul_f32_e32 v71, v110, v49
	v_mul_f32_e32 v73, 0.15915494, v71
	v_mul_f32_e32 v74, v111, v49
	v_rndne_f32_e32 v73, v73
	v_mul_f32_e32 v75, 0.15915494, v74
	v_fmac_f32_e32 v71, 0xc0c90000, v73
	v_rndne_f32_e32 v75, v75
	v_fmac_f32_e32 v71, 0xbafdaa22, v73
	v_fmac_f32_e32 v74, 0xc0c90000, v75
	v_mul_f32_e32 v73, 0.15915494, v71
	v_fmac_f32_e32 v74, 0xbafdaa22, v75
	v_sin_f32_e32 v71, v73
	v_mul_f32_e32 v75, 0.15915494, v74
	v_cos_f32_e32 v73, v73
	v_sin_f32_e32 v74, v75
	v_cos_f32_e32 v76, v75
	v_mul_f32_e32 v75, v112, v49
	v_mul_f32_e32 v77, 0.15915494, v75
	v_rndne_f32_e32 v77, v77
	v_mul_f32_e32 v78, v113, v49
	v_fmac_f32_e32 v75, 0xc0c90000, v77
	v_mul_f32_e32 v79, 0.15915494, v78
	v_fmac_f32_e32 v75, 0xbafdaa22, v77
	v_rndne_f32_e32 v79, v79
	v_mul_f32_e32 v77, 0.15915494, v75
	v_fmac_f32_e32 v78, 0xc0c90000, v79
	v_sin_f32_e32 v75, v77
	v_fmac_f32_e32 v78, 0xbafdaa22, v79
	v_cos_f32_e32 v77, v77
	v_mul_f32_e32 v79, 0.15915494, v78
	v_sin_f32_e32 v78, v79
	v_cos_f32_e32 v80, v79
	s_waitcnt vmcnt(0)
; #define LAS __attribute__((address_space(3)))
; __device__ __forceinline__ unsigned pk2(float lo, float hi) { return pg8::cvt_pk_bf16(lo, hi); }
; __device__ __forceinline__ float bflo(unsigned w) { return __uint_as_float(w << 16); }
; __device__ __forceinline__ float bfhi(unsigned w) { return __uint_as_float(w & 0xffff0000u); }
; __device__ __forceinline__ float fexp2(float x) { return __builtin_amdgcn_exp2f(x); }
; __device__ __forceinline__ void ret_unit(LAS unsigned char* lds, int u, const bf16* PROJ, const int* pos, const float* dec_f, const float* dec_b, const bf16* ST,
;                                          const float* gn_w, const float* gn_b, bf16* MIX, int tid, const WsRef& wsr) {
;     ...
;     for (int ii = 0; ii < 2; ++ii) { const int it = tid + 512 * ii, dc = it & 7, j = it >> 3;
;         const u32x4 q1 = rq1[ii], q2 = rq2[ii], k1 = rk1[ii], k2 = rk2[ii];
;         const float p = rp[ii];
;         float sn[8], cs[8];
; #pragma unroll
;         for (int e = 0; e < 8; ++e) { const int i = dc * 8 + e; const float inv = fexp2(-(float)i * 0.20762050593046015f); fast_sincos(p * inv, sn[e], cs[e]); }
;         u32x4 oq1, oq2, ok1, ok2;
; #pragma unroll
;         for (int e = 0; e < 4; ++e) { const int e0 = 2 * e, e1 = 2 * e + 1;
;             const float a0 = bflo(q1[e]), a1 = bfhi(q1[e]), b0 = bflo(q2[e]), b1 = bfhi(q2[e]);
;             oq1[e] = pk2(a0 * cs[e0] - b0 * sn[e0], a1 * cs[e1] - b1 * sn[e1]); oq2[e] = pk2(b0 * cs[e0] + a0 * sn[e0], b1 * cs[e1] + a1 * sn[e1]);
;             const float c0 = bflo(k1[e]) * 0.08838834764831845f, c1 = bfhi(k1[e]) * 0.08838834764831845f, d0 = bflo(k2[e]) * 0.08838834764831845f, d1 = bfhi(k2[e]) * 0.08838834764831845f;
;             ok1[e] = pk2(c0 * cs[e0] - d0 * sn[e0], c1 * cs[e1] - d1 * sn[e1]); ok2[e] = pk2(d0 * cs[e0] + c0 * sn[e0], d1 * cs[e1] + c1 * sn[e1]); }
;         *(LAS u32x4*)(Qs + j * LDT + dc * 8) = oq1; *(LAS u32x4*)(Qs + j * LDT + 64 + dc * 8) = oq2;
;         *(LAS u32x4*)(Ks + j * LDT + dc * 8) = ok1; *(LAS u32x4*)(Ks + j * LDT + 64 + dc * 8) = ok2; }
	v_cvt_f32_i32_e32 v88, v66
	v_mul_f32_e32 v66, v107, v49
	v_mul_f32_e32 v67, 0.15915494, v66
	v_rndne_f32_e32 v67, v67
	v_fmac_f32_e32 v66, 0xc0c90000, v67
	v_fmac_f32_e32 v66, 0xbafdaa22, v67
	v_mul_f32_e32 v67, 0.15915494, v66
	v_sin_f32_e32 v66, v67
	v_cos_f32_e32 v68, v67
	v_mul_f32_e32 v67, v108, v49
	v_mul_f32_e32 v69, 0.15915494, v67
	v_rndne_f32_e32 v69, v69
	v_fmac_f32_e32 v67, 0xc0c90000, v69
	v_fmac_f32_e32 v67, 0xbafdaa22, v69
	v_mul_f32_e32 v69, 0.15915494, v67
	v_sin_f32_e32 v67, v69
	v_cos_f32_e32 v69, v69
	v_mul_f32_e32 v49, v114, v49
	v_mul_f32_e32 v79, 0.15915494, v49
	v_pk_mul_f32 v[86:87], v[66:67], v[84:85]
	v_rndne_f32_e32 v79, v79
	v_pk_fma_f32 v[86:87], v[68:69], v[82:83], v[86:87] neg_lo:[0,0,1] neg_hi:[0,0,1]
	v_pk_mul_f32 v[82:83], v[66:67], v[82:83]
	v_cvt_pk_bf16_f32 v50, v86, v87
	v_pk_fma_f32 v[82:83], v[68:69], v[84:85], v[82:83]
	v_lshlrev_b32_e32 v84, 16, v62
	v_cvt_pk_bf16_f32 v54, v82, v83
	v_lshlrev_b32_e32 v82, 16, v58
	v_and_b32_e32 v83, 0xffff0000, v58
	v_and_b32_e32 v85, 0xffff0000, v62
	v_pk_mul_f32 v[82:83], v[82:83], s[10:11] op_sel_hi:[1,0]
	v_pk_mul_f32 v[84:85], v[84:85], s[10:11] op_sel_hi:[1,0]
	v_fmac_f32_e32 v49, 0xc0c90000, v79
	v_pk_mul_f32 v[86:87], v[84:85], v[66:67]
	v_pk_mul_f32 v[66:67], v[82:83], v[66:67]
	v_pk_fma_f32 v[86:87], v[82:83], v[68:69], v[86:87] neg_lo:[0,0,1] neg_hi:[0,0,1]
	v_pk_fma_f32 v[66:67], v[84:85], v[68:69], v[66:67]
	v_lshlrev_b32_e32 v68, 16, v55
	v_and_b32_e32 v69, 0xffff0000, v55
	v_cvt_pk_bf16_f32 v62, v66, v67
	v_lshlrev_b32_e32 v66, 16, v51
	v_and_b32_e32 v67, 0xffff0000, v51
	v_pk_mul_f32 v[82:83], v[70:71], v[68:69]
	v_fmac_f32_e32 v49, 0xbafdaa22, v79
	v_pk_fma_f32 v[82:83], v[72:73], v[66:67], v[82:83] neg_lo:[0,0,1] neg_hi:[0,0,1]
	v_pk_mul_f32 v[66:67], v[70:71], v[66:67]
	v_cvt_pk_bf16_f32 v51, v82, v83
	v_pk_fma_f32 v[66:67], v[72:73], v[68:69], v[66:67]
	v_lshlrev_b32_e32 v68, 16, v63
	v_and_b32_e32 v69, 0xffff0000, v63
	v_cvt_pk_bf16_f32 v55, v66, v67
	v_lshlrev_b32_e32 v66, 16, v59
	v_and_b32_e32 v67, 0xffff0000, v59
	v_pk_mul_f32 v[68:69], v[68:69], s[10:11] op_sel_hi:[1,0]
	v_pk_mul_f32 v[66:67], v[66:67], s[10:11] op_sel_hi:[1,0]
	v_pk_mul_f32 v[82:83], v[68:69], v[70:71]
	v_mul_f32_e32 v49, 0.15915494, v49
	v_pk_fma_f32 v[82:83], v[66:67], v[72:73], v[82:83] neg_lo:[0,0,1] neg_hi:[0,0,1]
	v_pk_mul_f32 v[66:67], v[66:67], v[70:71]
	v_sin_f32_e32 v79, v49
	v_pk_fma_f32 v[66:67], v[68:69], v[72:73], v[66:67]
	v_lshlrev_b32_e32 v68, 16, v56
	v_and_b32_e32 v69, 0xffff0000, v56
	v_cvt_pk_bf16_f32 v63, v66, v67
	v_lshlrev_b32_e32 v66, 16, v52
	v_and_b32_e32 v67, 0xffff0000, v52
	v_pk_mul_f32 v[70:71], v[74:75], v[68:69]
	v_cos_f32_e32 v81, v49
	v_pk_fma_f32 v[70:71], v[76:77], v[66:67], v[70:71] neg_lo:[0,0,1] neg_hi:[0,0,1]
	v_pk_mul_f32 v[66:67], v[74:75], v[66:67]
	v_cvt_pk_bf16_f32 v52, v70, v71
	v_pk_fma_f32 v[66:67], v[76:77], v[68:69], v[66:67]
	v_lshlrev_b32_e32 v68, 16, v64
	v_and_b32_e32 v69, 0xffff0000, v64
	v_cvt_pk_bf16_f32 v56, v66, v67
	v_lshlrev_b32_e32 v66, 16, v60
	v_and_b32_e32 v67, 0xffff0000, v60
	v_pk_mul_f32 v[68:69], v[68:69], s[10:11] op_sel_hi:[1,0]
	v_pk_mul_f32 v[66:67], v[66:67], s[10:11] op_sel_hi:[1,0]
	v_pk_mul_f32 v[70:71], v[68:69], v[74:75]
	v_mul_f32_e32 v49, v107, v88
	v_pk_fma_f32 v[70:71], v[66:67], v[76:77], v[70:71] neg_lo:[0,0,1] neg_hi:[0,0,1]
	v_pk_mul_f32 v[66:67], v[66:67], v[74:75]
	v_cvt_pk_bf16_f32 v60, v70, v71
	v_pk_fma_f32 v[66:67], v[68:69], v[76:77], v[66:67]
	v_lshlrev_b32_e32 v68, 16, v57
	v_and_b32_e32 v69, 0xffff0000, v57
	v_cvt_pk_bf16_f32 v64, v66, v67
	v_lshlrev_b32_e32 v66, 16, v53
	v_and_b32_e32 v67, 0xffff0000, v53
	v_pk_mul_f32 v[70:71], v[78:79], v[68:69]
	v_cvt_pk_bf16_f32 v58, v86, v87
	v_pk_fma_f32 v[70:71], v[80:81], v[66:67], v[70:71] neg_lo:[0,0,1] neg_hi:[0,0,1]
	v_pk_mul_f32 v[66:67], v[78:79], v[66:67]
	v_cvt_pk_bf16_f32 v53, v70, v71
	v_pk_fma_f32 v[66:67], v[80:81], v[68:69], v[66:67]
	v_lshlrev_b32_e32 v68, 16, v65
	v_and_b32_e32 v69, 0xffff0000, v65
	v_cvt_pk_bf16_f32 v57, v66, v67
	v_lshlrev_b32_e32 v66, 16, v61
	v_and_b32_e32 v67, 0xffff0000, v61
	v_pk_mul_f32 v[68:69], v[68:69], s[10:11] op_sel_hi:[1,0]
	v_pk_mul_f32 v[66:67], v[66:67], s[10:11] op_sel_hi:[1,0]
	v_pk_mul_f32 v[70:71], v[68:69], v[78:79]
	v_cvt_pk_bf16_f32 v59, v82, v83
	v_pk_fma_f32 v[70:71], v[66:67], v[80:81], v[70:71] neg_lo:[0,0,1] neg_hi:[0,0,1]
	v_pk_mul_f32 v[66:67], v[66:67], v[78:79]
	v_cvt_pk_bf16_f32 v61, v70, v71
	v_pk_fma_f32 v[66:67], v[68:69], v[80:81], v[66:67]
	v_lshlrev_b32_e32 v68, 16, v40
	v_cvt_pk_bf16_f32 v65, v66, v67
	ds_write_b128 v115, v[50:53]
	ds_write_b128 v115, v[54:57] offset:128
	ds_write_b128 v115, v[58:61] offset:34816
	ds_write_b128 v115, v[62:65] offset:34944
	v_mul_f32_e32 v50, 0.15915494, v49
	v_rndne_f32_e32 v50, v50
	v_fmac_f32_e32 v49, 0xc0c90000, v50
	v_fmac_f32_e32 v49, 0xbafdaa22, v50
	v_mul_f32_e32 v49, 0.15915494, v49
	v_sin_f32_e32 v50, v49
	v_cos_f32_e32 v52, v49
	v_mul_f32_e32 v49, v108, v88
	v_mul_f32_e32 v51, 0.15915494, v49
	v_rndne_f32_e32 v51, v51
	v_fmac_f32_e32 v49, 0xc0c90000, v51
	v_fmac_f32_e32 v49, 0xbafdaa22, v51
	v_mul_f32_e32 v49, 0.15915494, v49
	v_sin_f32_e32 v51, v49
	v_cos_f32_e32 v53, v49
	v_mul_f32_e32 v49, v109, v88
	v_mul_f32_e32 v54, 0.15915494, v49
	v_rndne_f32_e32 v54, v54
	v_fmac_f32_e32 v49, 0xc0c90000, v54
	v_fmac_f32_e32 v49, 0xbafdaa22, v54
	v_mul_f32_e32 v49, 0.15915494, v49
	v_sin_f32_e32 v54, v49
	v_cos_f32_e32 v56, v49
	v_mul_f32_e32 v49, v110, v88
	v_mul_f32_e32 v55, 0.15915494, v49
	v_rndne_f32_e32 v55, v55
	v_fmac_f32_e32 v49, 0xc0c90000, v55
	v_fmac_f32_e32 v49, 0xbafdaa22, v55
	v_mul_f32_e32 v49, 0.15915494, v49
; #define LAS __attribute__((address_space(3)))
; __device__ __forceinline__ unsigned pk2(float lo, float hi) { return pg8::cvt_pk_bf16(lo, hi); }
; __device__ __forceinline__ float bflo(unsigned w) { return __uint_as_float(w << 16); }
; __device__ __forceinline__ float bfhi(unsigned w) { return __uint_as_float(w & 0xffff0000u); }
; __device__ __forceinline__ u32x4 ws_load16(const WsRef& w, unsigned byte_off) { return __builtin_bit_cast(u32x4, __builtin_amdgcn_raw_buffer_load_b128(w.r, byte_off, 0, 0)); }
; __device__ __forceinline__ float fexp2(float x) { return __builtin_amdgcn_exp2f(x); }
; __device__ __forceinline__ void ret_unit(LAS unsigned char* lds, int u, const bf16* PROJ, const int* pos, const float* dec_f, const float* dec_b, const bf16* ST,
;                                          const float* gn_w, const float* gn_b, bf16* MIX, int tid, const WsRef& wsr) {
;     ...
;         for (int e = 0; e < 8; ++e) { const int i = dc * 8 + e; const float inv = fexp2(-(float)i * 0.20762050593046015f); fast_sincos(p * inv, sn[e], cs[e]); }
;         u32x4 oq1, oq2, ok1, ok2;
; #pragma unroll
;         for (int e = 0; e < 4; ++e) { const int e0 = 2 * e, e1 = 2 * e + 1;
;             const float a0 = bflo(q1[e]), a1 = bfhi(q1[e]), b0 = bflo(q2[e]), b1 = bfhi(q2[e]);
;             oq1[e] = pk2(a0 * cs[e0] - b0 * sn[e0], a1 * cs[e1] - b1 * sn[e1]); oq2[e] = pk2(b0 * cs[e0] + a0 * sn[e0], b1 * cs[e1] + a1 * sn[e1]);
;             const float c0 = bflo(k1[e]) * 0.08838834764831845f, c1 = bfhi(k1[e]) * 0.08838834764831845f, d0 = bflo(k2[e]) * 0.08838834764831845f, d1 = bfhi(k2[e]) * 0.08838834764831845f;
;             ok1[e] = pk2(c0 * cs[e0] - d0 * sn[e0], c1 * cs[e1] - d1 * sn[e1]); ok2[e] = pk2(d0 * cs[e0] + c0 * sn[e0], d1 * cs[e1] + c1 * sn[e1]); }
;         *(LAS u32x4*)(Qs + j * LDT + dc * 8) = oq1; *(LAS u32x4*)(Qs + j * LDT + 64 + dc * 8) = oq2;
;         *(LAS u32x4*)(Ks + j * LDT + dc * 8) = ok1; *(LAS u32x4*)(Ks + j * LDT + 64 + dc * 8) = ok2; }
; #pragma unroll
;     for (int ii = 0; ii < 4; ++ii) { const int it = tid + 512 * ii, ec = it & 15, j = it >> 4; rv[ii] = ws_load16(wsr, (unsigned)WS_PROJ + (unsigned)(((unsigned)(row0 + j) * INC + 1024 + h * 128 + ec * 8) * 2u)); }
	v_sin_f32_e32 v55, v49
	v_cos_f32_e32 v57, v49
	v_mul_f32_e32 v49, v111, v88
	v_mul_f32_e32 v58, 0.15915494, v49
	v_rndne_f32_e32 v58, v58
	v_fmac_f32_e32 v49, 0xc0c90000, v58
	v_fmac_f32_e32 v49, 0xbafdaa22, v58
	v_mul_f32_e32 v49, 0.15915494, v49
	v_sin_f32_e32 v58, v49
	v_cos_f32_e32 v60, v49
	v_mul_f32_e32 v49, v112, v88
	v_and_b32_e32 v69, 0xffff0000, v40
	v_mul_f32_e32 v59, 0.15915494, v49
	v_lshlrev_b32_e32 v66, 16, v44
	v_and_b32_e32 v67, 0xffff0000, v44
	v_pk_mul_f32 v[70:71], v[50:51], v[68:69]
	v_rndne_f32_e32 v59, v59
	v_pk_fma_f32 v[70:71], v[52:53], v[66:67], v[70:71] neg_lo:[0,0,1] neg_hi:[0,0,1]
	v_pk_mul_f32 v[66:67], v[50:51], v[66:67]
	v_fmac_f32_e32 v49, 0xc0c90000, v59
	v_pk_fma_f32 v[66:67], v[52:53], v[68:69], v[66:67]
	v_fmac_f32_e32 v49, 0xbafdaa22, v59
	v_cvt_pk_bf16_f32 v44, v66, v67
	v_lshlrev_b32_e32 v66, 16, v28
	v_and_b32_e32 v67, 0xffff0000, v28
	v_lshlrev_b32_e32 v68, 16, v0
	v_and_b32_e32 v69, 0xffff0000, v0
	v_mul_f32_e32 v49, 0.15915494, v49
	v_pk_mul_f32 v[66:67], v[66:67], s[10:11] op_sel_hi:[1,0]
	v_pk_mul_f32 v[68:69], v[68:69], s[10:11] op_sel_hi:[1,0]
	v_sin_f32_e32 v59, v49
	v_cos_f32_e32 v61, v49
	v_mul_f32_e32 v49, v113, v88
	v_cvt_pk_bf16_f32 v40, v70, v71
	v_pk_mul_f32 v[70:71], v[68:69], v[50:51]
	v_pk_mul_f32 v[50:51], v[66:67], v[50:51]
	v_mul_f32_e32 v62, 0.15915494, v49
	v_pk_fma_f32 v[70:71], v[66:67], v[52:53], v[70:71] neg_lo:[0,0,1] neg_hi:[0,0,1]
	v_pk_fma_f32 v[50:51], v[68:69], v[52:53], v[50:51]
	v_lshlrev_b32_e32 v52, 16, v41
	v_and_b32_e32 v53, 0xffff0000, v41
	v_rndne_f32_e32 v62, v62
	v_cvt_pk_bf16_f32 v28, v50, v51
	v_lshlrev_b32_e32 v50, 16, v45
	v_and_b32_e32 v51, 0xffff0000, v45
	v_pk_mul_f32 v[66:67], v[54:55], v[52:53]
	v_fmac_f32_e32 v49, 0xc0c90000, v62
	v_pk_fma_f32 v[66:67], v[56:57], v[50:51], v[66:67] neg_lo:[0,0,1] neg_hi:[0,0,1]
	v_pk_mul_f32 v[50:51], v[54:55], v[50:51]
	v_fmac_f32_e32 v49, 0xbafdaa22, v62
	v_pk_fma_f32 v[50:51], v[56:57], v[52:53], v[50:51]
	v_lshlrev_b32_e32 v52, 16, v1
	v_and_b32_e32 v53, 0xffff0000, v1
	v_mul_f32_e32 v49, 0.15915494, v49
	v_cvt_pk_bf16_f32 v45, v50, v51
	v_lshlrev_b32_e32 v50, 16, v29
	v_and_b32_e32 v51, 0xffff0000, v29
	v_pk_mul_f32 v[52:53], v[52:53], s[10:11] op_sel_hi:[1,0]
	v_sin_f32_e32 v62, v49
	v_cos_f32_e32 v64, v49
	v_mul_f32_e32 v49, v114, v88
	v_cvt_pk_bf16_f32 v41, v66, v67
	v_pk_mul_f32 v[50:51], v[50:51], s[10:11] op_sel_hi:[1,0]
	v_pk_mul_f32 v[66:67], v[52:53], v[54:55]
	v_mul_f32_e32 v63, 0.15915494, v49
	v_pk_fma_f32 v[66:67], v[50:51], v[56:57], v[66:67] neg_lo:[0,0,1] neg_hi:[0,0,1]
	v_pk_mul_f32 v[50:51], v[50:51], v[54:55]
	v_rndne_f32_e32 v63, v63
	v_pk_fma_f32 v[50:51], v[52:53], v[56:57], v[50:51]
	v_lshlrev_b32_e32 v52, 16, v42
	v_and_b32_e32 v53, 0xffff0000, v42
	v_fmac_f32_e32 v49, 0xc0c90000, v63
	v_cvt_pk_bf16_f32 v29, v50, v51
	v_lshlrev_b32_e32 v50, 16, v46
	v_and_b32_e32 v51, 0xffff0000, v46
	v_pk_mul_f32 v[54:55], v[58:59], v[52:53]
	v_fmac_f32_e32 v49, 0xbafdaa22, v63
	v_pk_fma_f32 v[54:55], v[60:61], v[50:51], v[54:55] neg_lo:[0,0,1] neg_hi:[0,0,1]
	v_pk_mul_f32 v[50:51], v[58:59], v[50:51]
	v_mul_f32_e32 v49, 0.15915494, v49
	v_pk_fma_f32 v[50:51], v[60:61], v[52:53], v[50:51]
	v_lshlrev_b32_e32 v52, 16, v2
	v_and_b32_e32 v53, 0xffff0000, v2
	v_sin_f32_e32 v63, v49
	v_cvt_pk_bf16_f32 v46, v50, v51
	v_lshlrev_b32_e32 v50, 16, v30
	v_and_b32_e32 v51, 0xffff0000, v30
	v_pk_mul_f32 v[52:53], v[52:53], s[10:11] op_sel_hi:[1,0]
	v_cos_f32_e32 v65, v49
	v_cvt_pk_bf16_f32 v42, v54, v55
	v_pk_mul_f32 v[50:51], v[50:51], s[10:11] op_sel_hi:[1,0]
	v_pk_mul_f32 v[54:55], v[52:53], v[58:59]
	v_cvt_pk_bf16_f32 v0, v70, v71
	v_pk_fma_f32 v[54:55], v[50:51], v[60:61], v[54:55] neg_lo:[0,0,1] neg_hi:[0,0,1]
	v_pk_mul_f32 v[50:51], v[50:51], v[58:59]
	v_cvt_pk_bf16_f32 v2, v54, v55
	v_pk_fma_f32 v[50:51], v[52:53], v[60:61], v[50:51]
	v_lshlrev_b32_e32 v52, 16, v43
	v_and_b32_e32 v53, 0xffff0000, v43
	v_cvt_pk_bf16_f32 v30, v50, v51
	v_lshlrev_b32_e32 v50, 16, v47
	v_and_b32_e32 v51, 0xffff0000, v47
	v_pk_mul_f32 v[54:55], v[62:63], v[52:53]
	v_cvt_pk_bf16_f32 v1, v66, v67
	v_pk_fma_f32 v[54:55], v[64:65], v[50:51], v[54:55] neg_lo:[0,0,1] neg_hi:[0,0,1]
	v_pk_mul_f32 v[50:51], v[62:63], v[50:51]
	v_cvt_pk_bf16_f32 v43, v54, v55
	v_pk_fma_f32 v[50:51], v[64:65], v[52:53], v[50:51]
	v_lshlrev_b32_e32 v52, 16, v3
	v_and_b32_e32 v53, 0xffff0000, v3
	v_cvt_pk_bf16_f32 v47, v50, v51
	v_lshlrev_b32_e32 v50, 16, v31
	v_and_b32_e32 v51, 0xffff0000, v31
	v_pk_mul_f32 v[52:53], v[52:53], s[10:11] op_sel_hi:[1,0]
	v_pk_mul_f32 v[50:51], v[50:51], s[10:11] op_sel_hi:[1,0]
	v_pk_mul_f32 v[54:55], v[52:53], v[62:63]
	v_add_u32_e32 v49, v124, v125
	v_pk_fma_f32 v[54:55], v[50:51], v[64:65], v[54:55] neg_lo:[0,0,1] neg_hi:[0,0,1]
	v_pk_mul_f32 v[50:51], v[50:51], v[62:63]
	v_cvt_pk_bf16_f32 v3, v54, v55
	v_pk_fma_f32 v[50:51], v[52:53], v[64:65], v[50:51]
	v_cndmask_b32_e64 v86, v105, v230, s[66:67]
	v_cvt_pk_bf16_f32 v31, v50, v51
	ds_write_b128 v116, v[40:43]
	ds_write_b128 v116, v[44:47] offset:128
	ds_write_b128 v116, v[0:3] offset:34816
	ds_write_b128 v116, v[28:31] offset:34944
	v_or_b32_e32 v44, s0, v222
	v_or_b32_e32 v0, s4, v99
	v_mad_u64_u32 v[0:1], s[68:69], v0, s9, v[44:45]
	v_lshl_add_u32 v0, v0, 1, v229
	buffer_load_dwordx4 v[0:3], v0, s[88:91], 0 offen
	v_or_b32_e32 v28, s4, v117
	v_mad_u64_u32 v[28:29], s[68:69], v28, s9, v[44:45]
	v_lshl_add_u32 v28, v28, 1, v229
	buffer_load_dwordx4 v[28:31], v28, s[88:91], 0 offen
	v_or_b32_e32 v40, s4, v118
	v_mad_u64_u32 v[40:41], s[68:69], v40, s9, v[44:45]
	v_lshl_add_u32 v40, v40, 1, v229
	buffer_load_dwordx4 v[40:43], v40, s[88:91], 0 offen
	v_add_u32_e32 v45, s4, v119
	v_mad_u64_u32 v[44:45], s[68:69], v45, s9, v[44:45]
	v_lshl_add_u32 v44, v44, 1, v229
	buffer_load_dwordx4 v[44:47], v44, s[88:91], 0 offen
	s_waitcnt vmcnt(3)
; #define LAS __attribute__((address_space(3)))
; __device__ __forceinline__ float fexp2(float x) { return __builtin_amdgcn_exp2f(x); }
; #define MFMA16(a, b, c) __builtin_amdgcn_mfma_f32_16x16x32_bf16((a), (b), (c), 0, 0, 0)
; __device__ __forceinline__ void ret_unit(LAS unsigned char* lds, int u, const bf16* PROJ, const int* pos, const float* dec_f, const float* dec_b, const bf16* ST,
;                                          const float* gn_w, const float* gn_b, bf16* MIX, int tid, const WsRef& wsr) {
;     ...
;     for (int ii = 0; ii < 4; ++ii) { const int it = tid + 512 * ii, ec = it & 15, j = it >> 4; const u32x4 w = rv[ii];
;         const int jsw = (((j >> 3) ^ (ec & 7)) << 3) | (j & 7);
; #pragma unroll
;         for (int e = 0; e < 4; ++e) { VT[(ec * 8 + 2 * e) * LDT + jsw] = (bf16)(w[e] & 0xffffu); VT[(ec * 8 + 2 * e + 1) * LDT + jsw] = (bf16)(w[e] >> 16); } }
;     __syncthreads();
;     const int q = wave * 16 + fr;
;     bf16x8 qf[4];
; #pragma unroll
;     for (int kk = 0; kk < 4; ++kk) qf[kk] = *(const LAS bf16x8*)(Qs + q * LDT + kk * 32 + fq * 8);
;     f32x4 s[8];
; #pragma unroll
;     for (int n = 0; n < 8; ++n) s[n] = (f32x4){0.f, 0.f, 0.f, 0.f};
; #pragma unroll
;     for (int kk = 0; kk < 4; ++kk)
; #pragma unroll
;         for (int n = 0; n < 8; ++n) { const bf16x8 kf = *(const LAS bf16x8*)(Ks + (n * 16 + fr) * LDT + kk * 32 + fq * 8); s[n] = MFMA16(kf, qf[kk], s[n]); }
;     ...
;         for (int r = 0; r < 4; ++r) { const int key = n * 16 + 4 * fq + r; const int df = q - key; const float f = df >= 0 ? fexp2(lgf2 * (float)df) : fexp2(lgb2 * (float)(-df)); s[n][r] *= f; } }
	ds_write_b16 v120, v0
	ds_write_b16_d16_hi v120, v0 offset:272
	ds_write_b16 v120, v1 offset:544
	ds_write_b16_d16_hi v120, v1 offset:816
	ds_write_b16 v120, v2 offset:1088
	ds_write_b16_d16_hi v120, v2 offset:1360
	ds_write_b16 v120, v3 offset:1632
	ds_write_b16_d16_hi v120, v3 offset:1904
	s_waitcnt vmcnt(2)
	ds_write_b16 v121, v28
	ds_write_b16_d16_hi v121, v28 offset:272
	ds_write_b16 v121, v29 offset:544
	ds_write_b16_d16_hi v121, v29 offset:816
	ds_write_b16 v121, v30 offset:1088
	ds_write_b16_d16_hi v121, v30 offset:1360
	ds_write_b16 v121, v31 offset:1632
	ds_write_b16_d16_hi v121, v31 offset:1904
	s_waitcnt vmcnt(1)
	ds_write_b16 v122, v40
	ds_write_b16_d16_hi v122, v40 offset:272
	ds_write_b16 v122, v41 offset:544
	ds_write_b16_d16_hi v122, v41 offset:816
	ds_write_b16 v122, v42 offset:1088
	ds_write_b16_d16_hi v122, v42 offset:1360
	ds_write_b16 v122, v43 offset:1632
	ds_write_b16_d16_hi v122, v43 offset:1904
	s_waitcnt vmcnt(0)
	ds_write_b16 v123, v44
	ds_write_b16_d16_hi v123, v44 offset:272
	ds_write_b16 v123, v45 offset:544
	ds_write_b16_d16_hi v123, v45 offset:816
	ds_write_b16 v123, v46 offset:1088
	ds_write_b16_d16_hi v123, v46 offset:1360
	ds_write_b16 v123, v47 offset:1632
	ds_write_b16_d16_hi v123, v47 offset:1904
	s_waitcnt lgkmcnt(0)
	s_barrier
	ds_read_b128 v[44:47], v225
	ds_read_b128 v[40:43], v225 offset:64
	ds_read_b128 v[28:31], v225 offset:128
	ds_read_b128 v[0:3], v225 offset:192
	ds_read_b128 v[50:53], v226 offset:34816
	ds_read_b128 v[54:57], v226 offset:39168
	ds_read_b128 v[82:85], v226 offset:34880
	s_waitcnt lgkmcnt(2)
	v_mfma_f32_16x16x32_bf16 v[50:53], v[50:53], v[44:47], 0
	ds_read_b128 v[58:61], v226 offset:43520
	ds_read_b128 v[62:65], v226 offset:47872
	ds_read_b128 v[66:69], v226 offset:52224
	s_waitcnt lgkmcnt(3)
	v_mfma_f32_16x16x32_bf16 v[50:53], v[82:85], v[40:43], v[50:53]
	ds_read_b128 v[82:85], v226 offset:39232
	ds_read_b128 v[70:73], v49 offset:34816
	ds_read_b128 v[74:77], v49 offset:39168
	v_mfma_f32_16x16x32_bf16 v[54:57], v[54:57], v[44:47], 0
	ds_read_b128 v[78:81], v49 offset:43520
	v_cndmask_b32_e64 v87, v105, v230, s[26:27]
	v_cndmask_b32_e64 v88, v105, v230, s[28:29]
	s_waitcnt lgkmcnt(3)
	v_mfma_f32_16x16x32_bf16 v[54:57], v[82:85], v[40:43], v[54:57]
	ds_read_b128 v[82:85], v226 offset:43584
	v_mul_f32_e32 v86, v86, v134
	v_mul_f32_e32 v87, v87, v135
	v_mfma_f32_16x16x32_bf16 v[58:61], v[58:61], v[44:47], 0
	v_mul_f32_e32 v88, v88, v136
	v_exp_f32_e32 v86, v86
	v_exp_f32_e32 v87, v87
	s_waitcnt lgkmcnt(0)
	v_mfma_f32_16x16x32_bf16 v[58:61], v[82:85], v[40:43], v[58:61]
	ds_read_b128 v[82:85], v226 offset:47936
	v_exp_f32_e32 v88, v88
	v_readlane_b32 s68, v255, 4
	v_mfma_f32_16x16x32_bf16 v[62:65], v[62:65], v[44:47], 0
	v_readlane_b32 s69, v255, 5
	s_waitcnt lgkmcnt(0)
	v_mfma_f32_16x16x32_bf16 v[62:65], v[82:85], v[40:43], v[62:65]
	ds_read_b128 v[82:85], v226 offset:52288
	v_cndmask_b32_e64 v239, v105, v230, s[68:69]
	v_readlane_b32 s68, v255, 50
	v_mfma_f32_16x16x32_bf16 v[66:69], v[66:69], v[44:47], 0
	v_readlane_b32 s69, v255, 51
	v_mul_f32_e32 v239, v239, v155
	v_exp_f32_e32 v239, v239
	s_waitcnt lgkmcnt(0)
	v_mfma_f32_16x16x32_bf16 v[66:69], v[82:85], v[40:43], v[66:69]
	ds_read_b128 v[82:85], v49 offset:34880
	v_cndmask_b32_e64 v240, v105, v230, s[68:69]
	v_readlane_b32 s68, v255, 52
	v_mfma_f32_16x16x32_bf16 v[70:73], v[70:73], v[44:47], 0
	v_readlane_b32 s69, v255, 53
	v_mul_f32_e32 v240, v240, v156
	v_exp_f32_e32 v240, v240
	s_waitcnt lgkmcnt(0)
	v_mfma_f32_16x16x32_bf16 v[70:73], v[82:85], v[40:43], v[70:73]
	ds_read_b128 v[82:85], v49 offset:39232
	v_cndmask_b32_e64 v241, v105, v230, s[68:69]
	v_readlane_b32 s68, v255, 54
	v_mfma_f32_16x16x32_bf16 v[74:77], v[74:77], v[44:47], 0
	v_readlane_b32 s69, v255, 55
	v_mul_f32_e32 v241, v241, v157
	v_exp_f32_e32 v241, v241
	s_waitcnt lgkmcnt(0)
	v_mfma_f32_16x16x32_bf16 v[74:77], v[82:85], v[40:43], v[74:77]
	ds_read_b128 v[82:85], v49 offset:43584
	v_cndmask_b32_e64 v242, v105, v230, s[68:69]
	v_readlane_b32 s68, v255, 56
	v_mfma_f32_16x16x32_bf16 v[78:81], v[78:81], v[44:47], 0
	v_readlane_b32 s69, v255, 57
	v_mul_f32_e32 v242, v242, v158
	v_exp_f32_e32 v242, v242
	s_waitcnt lgkmcnt(0)
	v_mfma_f32_16x16x32_bf16 v[78:81], v[82:85], v[40:43], v[78:81]
	ds_read_b128 v[82:85], v226 offset:34944
	v_cndmask_b32_e64 v243, v105, v230, s[68:69]
	v_mul_f32_e32 v243, v243, v159
	s_waitcnt lgkmcnt(0)
	v_mfma_f32_16x16x32_bf16 v[50:53], v[82:85], v[28:31], v[50:53]
	ds_read_b128 v[82:85], v226 offset:39296
	v_exp_f32_e32 v243, v243
	s_waitcnt lgkmcnt(0)
	v_mfma_f32_16x16x32_bf16 v[54:57], v[82:85], v[28:31], v[54:57]
	ds_read_b128 v[82:85], v226 offset:43648
	s_waitcnt lgkmcnt(0)
	v_mfma_f32_16x16x32_bf16 v[58:61], v[82:85], v[28:31], v[58:61]
	ds_read_b128 v[82:85], v226 offset:48000
	s_waitcnt lgkmcnt(0)
	v_mfma_f32_16x16x32_bf16 v[62:65], v[82:85], v[28:31], v[62:65]
	ds_read_b128 v[82:85], v226 offset:52352
	s_waitcnt lgkmcnt(0)
	v_mfma_f32_16x16x32_bf16 v[66:69], v[82:85], v[28:31], v[66:69]
	ds_read_b128 v[82:85], v49 offset:34944
	s_waitcnt lgkmcnt(0)
	v_mfma_f32_16x16x32_bf16 v[70:73], v[82:85], v[28:31], v[70:73]
	ds_read_b128 v[82:85], v49 offset:39296
	s_waitcnt lgkmcnt(0)
	v_mfma_f32_16x16x32_bf16 v[74:77], v[82:85], v[28:31], v[74:77]
	ds_read_b128 v[82:85], v49 offset:43648
	s_waitcnt lgkmcnt(0)
	v_mfma_f32_16x16x32_bf16 v[78:81], v[82:85], v[28:31], v[78:81]
	ds_read_b128 v[82:85], v226 offset:35008
	s_waitcnt lgkmcnt(0)
	v_mfma_f32_16x16x32_bf16 v[50:53], v[82:85], v[0:3], v[50:53]
	ds_read_b128 v[82:85], v226 offset:39360
	s_waitcnt lgkmcnt(0)
; #define LAS __attribute__((address_space(3)))
; __device__ __forceinline__ unsigned pk2(float lo, float hi) { return pg8::cvt_pk_bf16(lo, hi); }
; __device__ __forceinline__ float fexp2(float x) { return __builtin_amdgcn_exp2f(x); }
; #define MFMA16(a, b, c) __builtin_amdgcn_mfma_f32_16x16x32_bf16((a), (b), (c), 0, 0, 0)
; __device__ __forceinline__ void ret_unit(LAS unsigned char* lds, int u, const bf16* PROJ, const int* pos, const float* dec_f, const float* dec_b, const bf16* ST,
;                                          const float* gn_w, const float* gn_b, bf16* MIX, int tid, const WsRef& wsr) {
;     ...
;     for (int n = 0; n < 8; ++n) {
; #pragma unroll
;         for (int r = 0; r < 4; ++r) { const int key = n * 16 + 4 * fq + r; const int df = q - key; const float f = df >= 0 ? fexp2(lgf2 * (float)df) : fexp2(lgb2 * (float)(-df)); s[n][r] *= f; } }
; #pragma unroll
;     for (int kk = 0; kk < 4; ++kk) { u32x4 w; w.x = pk2(s[2 * kk][0], s[2 * kk][1]); w.y = pk2(s[2 * kk][2], s[2 * kk][3]); w.z = pk2(s[2 * kk + 1][0], s[2 * kk + 1][1]); w.w = pk2(s[2 * kk + 1][2], s[2 * kk + 1][3]);
;         pf[kk] = __builtin_bit_cast(bf16x8, w); }
;     f32x4 o[8];
; #pragma unroll
;     for (int n = 0; n < 8; ++n) o[n] = (f32x4){0.f, 0.f, 0.f, 0.f};
; #pragma unroll
;     for (int kk = 0; kk < 4; ++kk)
; #pragma unroll
;         for (int n = 0; n < 8; ++n) { const int sw = (2 * n + (fr >> 3)) & 7, jc = kk * 4 + (fq >> 1); const LAS bf16* vr = VT + (n * 16 + fr) * LDT + 4 * (fq & 1);
;             const u32x2 lo = *(const LAS u32x2*)(vr + ((jc ^ sw) << 3)), hi = *(const LAS u32x2*)(vr + (((jc + 2) ^ sw) << 3)); u32x4 w; w.x = lo.x; w.y = lo.y; w.z = hi.x; w.w = hi.y;
;             o[n] = MFMA16(__builtin_bit_cast(bf16x8, w), pf[kk], o[n]); }
	v_mfma_f32_16x16x32_bf16 v[54:57], v[82:85], v[0:3], v[54:57]
	ds_read_b128 v[82:85], v226 offset:43712
	s_nop 6
	v_pk_mul_f32 v[56:57], v[86:87], v[56:57]
	s_waitcnt lgkmcnt(0)
	v_mfma_f32_16x16x32_bf16 v[58:61], v[82:85], v[0:3], v[58:61]
	ds_read_b128 v[82:85], v226 offset:48064
	s_nop 6
	v_pk_mul_f32 v[58:59], v[88:89], v[58:59]
	s_waitcnt lgkmcnt(0)
	v_mfma_f32_16x16x32_bf16 v[62:65], v[82:85], v[0:3], v[62:65]
	ds_read_b128 v[82:85], v226 offset:52416
	v_pk_mul_f32 v[88:89], v[90:91], v[60:61]
	s_nop 5
	v_pk_mul_f32 v[64:65], v[94:95], v[64:65]
	s_waitcnt lgkmcnt(0)
	v_mfma_f32_16x16x32_bf16 v[66:69], v[82:85], v[0:3], v[66:69]
	ds_read_b128 v[82:85], v49 offset:35008
	v_pk_mul_f32 v[92:93], v[92:93], v[62:63]
	v_cvt_pk_bf16_f32 v63, v56, v57
	v_cvt_pk_bf16_f32 v56, v58, v59
	v_cvt_pk_bf16_f32 v59, v64, v65
	v_add_u32_e32 v64, v160, v161
	ds_read_b64 v[64:65], v64
	s_waitcnt lgkmcnt(1)
	v_mfma_f32_16x16x32_bf16 v[70:73], v[82:85], v[0:3], v[70:73]
	ds_read_b128 v[82:85], v49 offset:39360
	v_cvt_pk_bf16_f32 v58, v92, v93
	v_add_u32_e32 v92, v175, v170
	ds_read_b64 v[92:93], v92
	s_waitcnt lgkmcnt(1)
	v_mfma_f32_16x16x32_bf16 v[74:77], v[82:85], v[0:3], v[74:77]
	ds_read_b128 v[82:85], v49 offset:43712
	v_add_u32_e32 v94, v175, v171
	ds_read_b64 v[94:95], v94
	s_waitcnt lgkmcnt(1)
	v_mfma_f32_16x16x32_bf16 v[78:81], v[82:85], v[0:3], v[78:81]
	v_cndmask_b32_e64 v49, v105, v230, s[44:45]
	v_cndmask_b32_e64 v82, v105, v230, s[46:47]
	v_cndmask_b32_e64 v83, v105, v230, s[48:49]
	v_mul_f32_e32 v49, v49, v129
	v_mul_f32_e32 v82, v82, v231
	v_mul_f32_e32 v83, v83, v252
	v_exp_f32_e32 v49, v49
	v_exp_f32_e32 v82, v82
	v_exp_f32_e32 v83, v83
	v_pk_mul_f32 v[66:67], v[130:131], v[66:67]
	v_pk_mul_f32 v[48:49], v[48:49], v[50:51]
	v_cndmask_b32_e64 v84, v105, v230, s[50:51]
	v_pk_mul_f32 v[50:51], v[82:83], v[52:53]
	v_cvt_pk_bf16_f32 v52, v66, v67
	v_add_u32_e32 v66, v160, v162
	ds_read_b64 v[66:67], v66
	v_cndmask_b32_e64 v85, v105, v230, s[52:53]
	v_mul_f32_e32 v84, v84, v253
	v_mul_f32_e32 v85, v85, v254
	v_exp_f32_e32 v84, v84
	v_exp_f32_e32 v85, v85
	v_cvt_pk_bf16_f32 v60, v48, v49
	v_cvt_pk_bf16_f32 v61, v50, v51
	v_pk_mul_f32 v[80:81], v[242:243], v[80:81]
	v_pk_mul_f32 v[54:55], v[84:85], v[54:55]
	v_cvt_pk_bf16_f32 v51, v80, v81
	v_cvt_pk_bf16_f32 v62, v54, v55
	v_cvt_pk_bf16_f32 v57, v88, v89
	v_pk_mul_f32 v[78:79], v[240:241], v[78:79]
	s_waitcnt lgkmcnt(0)
	v_mfma_f32_16x16x32_bf16 v[84:87], v[64:67], v[60:63], 0
	v_add_u32_e32 v64, v163, v164
	v_add_u32_e32 v66, v163, v165
	ds_read_b64 v[64:65], v64
	ds_read_b64 v[66:67], v66
	s_waitcnt lgkmcnt(0)
	v_mfma_f32_16x16x32_bf16 v[80:83], v[64:67], v[60:63], 0
	v_add_u32_e32 v64, v166, v167
	v_add_u32_e32 v66, v166, v168
	ds_read_b64 v[64:65], v64
	ds_read_b64 v[66:67], v66
	s_waitcnt lgkmcnt(0)
	v_mfma_f32_16x16x32_bf16 v[88:91], v[64:67], v[60:63], 0
	v_add_u32_e32 v64, v169, v170
	v_add_u32_e32 v66, v169, v171
	ds_read_b64 v[64:65], v64
	ds_read_b64 v[66:67], v66
	v_pk_mul_f32 v[76:77], v[238:239], v[76:77]
	v_cvt_pk_bf16_f32 v50, v78, v79
	v_cvt_pk_bf16_f32 v49, v76, v77
	s_waitcnt lgkmcnt(0)
	v_mfma_f32_16x16x32_bf16 v[76:79], v[64:67], v[60:63], 0
	v_add_u32_e32 v64, v172, v161
	v_add_u32_e32 v66, v172, v162
	ds_read_b64 v[64:65], v64
	ds_read_b64 v[66:67], v66
	v_pk_mul_f32 v[74:75], v[236:237], v[74:75]
	v_pk_mul_f32 v[72:73], v[234:235], v[72:73]
	v_cvt_pk_bf16_f32 v48, v74, v75
	v_cvt_pk_bf16_f32 v55, v72, v73
	s_waitcnt lgkmcnt(0)
	v_mfma_f32_16x16x32_bf16 v[72:75], v[64:67], v[60:63], 0
	v_add_u32_e32 v64, v173, v164
	v_add_u32_e32 v66, v173, v165
	ds_read_b64 v[64:65], v64
	ds_read_b64 v[66:67], v66
	v_pk_mul_f32 v[70:71], v[232:233], v[70:71]
	v_pk_mul_f32 v[68:69], v[132:133], v[68:69]
	v_cvt_pk_bf16_f32 v54, v70, v71
	v_cvt_pk_bf16_f32 v53, v68, v69
	s_waitcnt lgkmcnt(0)
	v_mfma_f32_16x16x32_bf16 v[68:71], v[64:67], v[60:63], 0
	v_add_u32_e32 v64, v174, v167
	v_add_u32_e32 v66, v174, v168
	ds_read_b64 v[64:65], v64
	ds_read_b64 v[66:67], v66
	s_waitcnt lgkmcnt(0)
	v_mfma_f32_16x16x32_bf16 v[64:67], v[64:67], v[60:63], 0
	v_mfma_f32_16x16x32_bf16 v[60:63], v[92:95], v[60:63], 0
	v_add_u32_e32 v92, v160, v176
	v_add_u32_e32 v94, v160, v177
	ds_read_b64 v[92:93], v92
	ds_read_b64 v[94:95], v94
	s_waitcnt lgkmcnt(0)
	v_mfma_f32_16x16x32_bf16 v[84:87], v[92:95], v[56:59], v[84:87]
	v_add_u32_e32 v92, v163, v178
	v_add_u32_e32 v94, v163, v179
	ds_read_b64 v[92:93], v92
	ds_read_b64 v[94:95], v94
	s_waitcnt lgkmcnt(0)
	v_mfma_f32_16x16x32_bf16 v[80:83], v[92:95], v[56:59], v[80:83]
	v_add_u32_e32 v92, v166, v180
	v_add_u32_e32 v94, v166, v181
	ds_read_b64 v[92:93], v92
	ds_read_b64 v[94:95], v94
	s_waitcnt lgkmcnt(0)
	v_mfma_f32_16x16x32_bf16 v[88:91], v[92:95], v[56:59], v[88:91]
	v_add_u32_e32 v92, v169, v182
	v_add_u32_e32 v94, v169, v183
	ds_read_b64 v[92:93], v92
	ds_read_b64 v[94:95], v94
	s_waitcnt lgkmcnt(0)
	v_mfma_f32_16x16x32_bf16 v[92:95], v[92:95], v[56:59], v[76:79]
	s_nop 2
	v_add_u32_e32 v76, v172, v176
	v_add_u32_e32 v78, v172, v177
	ds_read_b64 v[76:77], v76
	ds_read_b64 v[78:79], v78
	s_waitcnt lgkmcnt(0)
	v_mfma_f32_16x16x32_bf16 v[72:75], v[76:79], v[56:59], v[72:75]
	v_add_u32_e32 v76, v173, v178
	v_add_u32_e32 v78, v173, v179
	ds_read_b64 v[76:77], v76
	ds_read_b64 v[78:79], v78
	s_waitcnt lgkmcnt(0)
	v_mfma_f32_16x16x32_bf16 v[68:71], v[76:79], v[56:59], v[68:71]
	v_add_u32_e32 v76, v174, v180
	v_add_u32_e32 v78, v174, v181
	ds_read_b64 v[76:77], v76
	ds_read_b64 v[78:79], v78
	s_waitcnt lgkmcnt(0)
	v_mfma_f32_16x16x32_bf16 v[64:67], v[76:79], v[56:59], v[64:67]
	v_add_u32_e32 v76, v175, v182
	v_add_u32_e32 v78, v175, v183
	ds_read_b64 v[76:77], v76
	ds_read_b64 v[78:79], v78
	s_waitcnt lgkmcnt(0)
; #define LAS __attribute__((address_space(3)))
; #define MFMA16(a, b, c) __builtin_amdgcn_mfma_f32_16x16x32_bf16((a), (b), (c), 0, 0, 0)
; __device__ __forceinline__ void ret_unit(LAS unsigned char* lds, int u, const bf16* PROJ, const int* pos, const float* dec_f, const float* dec_b, const bf16* ST,
;                                          const float* gn_w, const float* gn_b, bf16* MIX, int tid, const WsRef& wsr) {
;     ...
;         for (int n = 0; n < 8; ++n) { const int sw = (2 * n + (fr >> 3)) & 7, jc = kk * 4 + (fq >> 1); const LAS bf16* vr = VT + (n * 16 + fr) * LDT + 4 * (fq & 1);
;             const u32x2 lo = *(const LAS u32x2*)(vr + ((jc ^ sw) << 3)), hi = *(const LAS u32x2*)(vr + (((jc + 2) ^ sw) << 3)); u32x4 w; w.x = lo.x; w.y = lo.y; w.z = hi.x; w.w = hi.y;
;             o[n] = MFMA16(__builtin_bit_cast(bf16x8, w), pf[kk], o[n]); }
;     __syncthreads();
; #pragma unroll
;     for (int i = 0; i < 4; ++i) { const int id = tid + 512 * i, e = id >> 4, dch = id & 15;
;         *(LAS u32x4*)(Ks + e * LDT + dch * 8) = sf[i]; *(LAS u32x4*)(VT + e * LDT + dch * 8) = sb[i]; }
;     __syncthreads();
;     {
;         f32x4 tf[8], tb[8];
; #pragma unroll
;         for (int n = 0; n < 8; ++n) { tf[n] = (f32x4){0.f, 0.f, 0.f, 0.f}; tb[n] = (f32x4){0.f, 0.f, 0.f, 0.f}; }
; #pragma unroll
;         for (int kk = 0; kk < 4; ++kk)
; #pragma unroll
;             for (int n = 0; n < 8; ++n) { const bf16x8 yf = *(const LAS bf16x8*)(Ks + (n * 16 + fr) * LDT + kk * 32 + fq * 8); const bf16x8 yb = *(const LAS bf16x8*)(VT + (n * 16 + fr) * LDT + kk * 32 + fq * 8);
;                 tf[n] = MFMA16(yf, qf[kk], tf[n]); tb[n] = MFMA16(yb, qf[kk], tb[n]); }
	v_mfma_f32_16x16x32_bf16 v[56:59], v[76:79], v[56:59], v[60:63]
	v_add_u32_e32 v76, v163, v186
	v_add_u32_e32 v78, v163, v187
	ds_read_b64 v[76:77], v76
	ds_read_b64 v[78:79], v78
	s_waitcnt lgkmcnt(0)
	v_mfma_f32_16x16x32_bf16 v[76:79], v[76:79], v[52:55], v[80:83]
	s_nop 2
	v_add_u32_e32 v80, v166, v188
	v_add_u32_e32 v82, v166, v189
	ds_read_b64 v[80:81], v80
	ds_read_b64 v[82:83], v82
	s_waitcnt lgkmcnt(0)
	v_mfma_f32_16x16x32_bf16 v[80:83], v[80:83], v[52:55], v[88:91]
	s_nop 2
	v_add_u32_e32 v88, v172, v184
	v_add_u32_e32 v90, v172, v185
	ds_read_b64 v[88:89], v88
	ds_read_b64 v[90:91], v90
	s_waitcnt lgkmcnt(0)
	v_mfma_f32_16x16x32_bf16 v[72:75], v[88:91], v[52:55], v[72:75]
	v_add_u32_e32 v88, v173, v186
	v_add_u32_e32 v90, v173, v187
	v_add_u32_e32 v60, v160, v184
	v_add_u32_e32 v62, v160, v185
	ds_read_b64 v[88:89], v88
	ds_read_b64 v[90:91], v90
	ds_read_b64 v[60:61], v60
	ds_read_b64 v[62:63], v62
	s_waitcnt lgkmcnt(2)
	v_mfma_f32_16x16x32_bf16 v[88:91], v[88:91], v[52:55], v[68:71]
	s_nop 2
	v_add_u32_e32 v68, v174, v188
	v_add_u32_e32 v70, v174, v189
	ds_read_b64 v[68:69], v68
	ds_read_b64 v[70:71], v70
	s_waitcnt lgkmcnt(2)
	v_mfma_f32_16x16x32_bf16 v[60:63], v[60:63], v[52:55], v[84:87]
	s_nop 2
	v_add_u32_e32 v84, v169, v190
	v_add_u32_e32 v86, v169, v191
	ds_read_b64 v[84:85], v84
	ds_read_b64 v[86:87], v86
	s_waitcnt lgkmcnt(0)
	v_mfma_f32_16x16x32_bf16 v[84:87], v[84:87], v[52:55], v[92:95]
	v_mfma_f32_16x16x32_bf16 v[92:95], v[68:71], v[52:55], v[64:67]
	v_add_u32_e32 v68, v172, v192
	v_add_u32_e32 v70, v172, v193
	ds_read_b64 v[68:69], v68
	ds_read_b64 v[70:71], v70
	v_add_u32_e32 v64, v175, v190
	v_add_u32_e32 v66, v175, v191
	ds_read_b64 v[64:65], v64
	ds_read_b64 v[66:67], v66
	s_waitcnt lgkmcnt(0)
	v_mfma_f32_16x16x32_bf16 v[232:235], v[64:67], v[52:55], v[56:59]
	v_add_u32_e32 v52, v160, v192
	v_add_u32_e32 v54, v160, v193
	ds_read_b64 v[52:53], v52
	ds_read_b64 v[54:55], v54
	v_add_u32_e32 v56, v163, v194
	v_add_u32_e32 v58, v163, v195
	ds_read_b64 v[56:57], v56
	ds_read_b64 v[58:59], v58
	s_waitcnt lgkmcnt(2)
	v_mfma_f32_16x16x32_bf16 v[52:55], v[52:55], v[48:51], v[60:63]
	s_nop 2
	v_add_u32_e32 v60, v166, v196
	v_add_u32_e32 v62, v166, v197
	ds_read_b64 v[60:61], v60
	ds_read_b64 v[62:63], v62
	v_add_u32_e32 v64, v169, v198
	v_add_u32_e32 v66, v169, v199
	s_waitcnt lgkmcnt(2)
	v_mfma_f32_16x16x32_bf16 v[56:59], v[56:59], v[48:51], v[76:79]
	ds_read_b64 v[64:65], v64
	ds_read_b64 v[66:67], v66
	s_waitcnt lgkmcnt(2)
	v_mfma_f32_16x16x32_bf16 v[60:63], v[60:63], v[48:51], v[80:83]
	v_add_u32_e32 v76, v174, v196
	v_add_u32_e32 v78, v174, v197
	s_nop 0
	v_add_u32_e32 v80, v175, v198
	v_mfma_f32_16x16x32_bf16 v[68:71], v[68:71], v[48:51], v[72:75]
	v_add_u32_e32 v82, v175, v199
	ds_read_b64 v[76:77], v76
	ds_read_b64 v[78:79], v78
	v_add_u32_e32 v72, v173, v194
	v_add_u32_e32 v74, v173, v195
	ds_read_b64 v[72:73], v72
	ds_read_b64 v[74:75], v74
	ds_read_b64 v[80:81], v80
	ds_read_b64 v[82:83], v82
	s_waitcnt lgkmcnt(0)
	s_barrier
	ds_write_b128 v200, v[4:7] offset:34816
	ds_write_b128 v201, v[12:15]
	ds_write_b128 v202, v[8:11] offset:34816
	ds_write_b128 v203, v[16:19]
	ds_write_b128 v205, v[24:27] offset:34816
	ds_write_b128 v206, v[20:23]
	ds_write_b128 v207, v[32:35] offset:34816
	ds_write_b128 v208, v[36:39]
	s_waitcnt lgkmcnt(0)
	s_barrier
	ds_read_b128 v[4:7], v209 offset:34816
	ds_read_b128 v[8:11], v210
	s_waitcnt lgkmcnt(1)
	v_mfma_f32_16x16x32_bf16 v[12:15], v[4:7], v[44:47], 0
	s_waitcnt lgkmcnt(0)
	v_mfma_f32_16x16x32_bf16 v[16:19], v[8:11], v[44:47], 0
	ds_read_b128 v[4:7], v209 offset:39168
	ds_read_b128 v[8:11], v211
	s_waitcnt lgkmcnt(1)
	v_mfma_f32_16x16x32_bf16 v[32:35], v[4:7], v[44:47], 0
	s_waitcnt lgkmcnt(0)
	v_mfma_f32_16x16x32_bf16 v[36:39], v[8:11], v[44:47], 0
	ds_read_b128 v[4:7], v209 offset:43520
	ds_read_b128 v[8:11], v212
	v_mfma_f32_16x16x32_bf16 v[72:75], v[72:75], v[48:51], v[88:91]
	v_mfma_f32_16x16x32_bf16 v[76:79], v[76:79], v[48:51], v[92:95]
	s_waitcnt lgkmcnt(1)
	v_mfma_f32_16x16x32_bf16 v[88:91], v[4:7], v[44:47], 0
	s_waitcnt lgkmcnt(0)
	v_mfma_f32_16x16x32_bf16 v[92:95], v[8:11], v[44:47], 0
	ds_read_b128 v[4:7], v209 offset:47872
	ds_read_b128 v[8:11], v213
	v_mfma_f32_16x16x32_bf16 v[64:67], v[64:67], v[48:51], v[84:87]
	v_mfma_f32_16x16x32_bf16 v[48:51], v[80:83], v[48:51], v[232:235]
	s_waitcnt lgkmcnt(1)
	v_mfma_f32_16x16x32_bf16 v[232:235], v[4:7], v[44:47], 0
	s_waitcnt lgkmcnt(0)
	v_mfma_f32_16x16x32_bf16 v[236:239], v[8:11], v[44:47], 0
	ds_read_b128 v[4:7], v209 offset:52224
	ds_read_b128 v[8:11], v214
	s_waitcnt lgkmcnt(1)
	v_mfma_f32_16x16x32_bf16 v[240:243], v[4:7], v[44:47], 0
	s_waitcnt lgkmcnt(0)
	v_mfma_f32_16x16x32_bf16 v[244:247], v[8:11], v[44:47], 0
	ds_read_b128 v[4:7], v209 offset:56576
	ds_read_b128 v[8:11], v215
	s_waitcnt lgkmcnt(1)
	v_mfma_f32_16x16x32_bf16 v[80:83], v[4:7], v[44:47], 0
	s_waitcnt lgkmcnt(0)
	v_mfma_f32_16x16x32_bf16 v[84:87], v[8:11], v[44:47], 0
	ds_read_b128 v[4:7], v209 offset:60928
	ds_read_b128 v[8:11], v216
	s_waitcnt lgkmcnt(1)
	v_mfma_f32_16x16x32_bf16 v[20:23], v[4:7], v[44:47], 0
	ds_read_b128 v[4:7], v209 offset:65280
	ds_read_b128 v[248:251], v217
	s_waitcnt lgkmcnt(2)
	v_mfma_f32_16x16x32_bf16 v[24:27], v[8:11], v[44:47], 0
	s_waitcnt lgkmcnt(1)
	v_mfma_f32_16x16x32_bf16 v[8:11], v[4:7], v[44:47], 0
	s_waitcnt lgkmcnt(0)
	v_mfma_f32_16x16x32_bf16 v[4:7], v[248:251], v[44:47], 0
	ds_read_b128 v[44:47], v209 offset:34880
	ds_read_b128 v[248:251], v210 offset:64
	s_waitcnt lgkmcnt(1)
	v_mfma_f32_16x16x32_bf16 v[12:15], v[44:47], v[40:43], v[12:15]
	s_waitcnt lgkmcnt(0)
; #define LAS __attribute__((address_space(3)))
; #define MFMA16(a, b, c) __builtin_amdgcn_mfma_f32_16x16x32_bf16((a), (b), (c), 0, 0, 0)
; __device__ __forceinline__ void ret_unit(LAS unsigned char* lds, int u, const bf16* PROJ, const int* pos, const float* dec_f, const float* dec_b, const bf16* ST,
;                                          const float* gn_w, const float* gn_b, bf16* MIX, int tid, const WsRef& wsr) {
;     ...
;         for (int kk = 0; kk < 4; ++kk)
; #pragma unroll
;             for (int n = 0; n < 8; ++n) { const bf16x8 yf = *(const LAS bf16x8*)(Ks + (n * 16 + fr) * LDT + kk * 32 + fq * 8); const bf16x8 yb = *(const LAS bf16x8*)(VT + (n * 16 + fr) * LDT + kk * 32 + fq * 8);
;                 tf[n] = MFMA16(yf, qf[kk], tf[n]); tb[n] = MFMA16(yb, qf[kk], tb[n]); }
	v_mfma_f32_16x16x32_bf16 v[16:19], v[248:251], v[40:43], v[16:19]
	ds_read_b128 v[44:47], v209 offset:39232
	ds_read_b128 v[248:251], v211 offset:64
	s_waitcnt lgkmcnt(1)
	v_mfma_f32_16x16x32_bf16 v[32:35], v[44:47], v[40:43], v[32:35]
	s_waitcnt lgkmcnt(0)
	v_mfma_f32_16x16x32_bf16 v[36:39], v[248:251], v[40:43], v[36:39]
	ds_read_b128 v[44:47], v209 offset:43584
	ds_read_b128 v[248:251], v212 offset:64
	s_waitcnt lgkmcnt(1)
	v_mfma_f32_16x16x32_bf16 v[44:47], v[44:47], v[40:43], v[88:91]
	s_waitcnt lgkmcnt(0)
	v_mfma_f32_16x16x32_bf16 v[88:91], v[248:251], v[40:43], v[92:95]
	s_nop 2
	ds_read_b128 v[92:95], v209 offset:47936
	ds_read_b128 v[248:251], v213 offset:64
	s_waitcnt lgkmcnt(1)
	v_mfma_f32_16x16x32_bf16 v[92:95], v[92:95], v[40:43], v[232:235]
	s_waitcnt lgkmcnt(0)
	v_mfma_f32_16x16x32_bf16 v[232:235], v[248:251], v[40:43], v[236:239]
	s_nop 2
	ds_read_b128 v[236:239], v209 offset:52288
	ds_read_b128 v[248:251], v214 offset:64
	s_waitcnt lgkmcnt(1)
	v_mfma_f32_16x16x32_bf16 v[236:239], v[236:239], v[40:43], v[240:243]
	s_waitcnt lgkmcnt(0)
	v_mfma_f32_16x16x32_bf16 v[240:243], v[248:251], v[40:43], v[244:247]
	s_nop 2
	ds_read_b128 v[244:247], v209 offset:56640
	ds_read_b128 v[248:251], v215 offset:64
	s_waitcnt lgkmcnt(1)
	v_mfma_f32_16x16x32_bf16 v[80:83], v[244:247], v[40:43], v[80:83]
	s_waitcnt lgkmcnt(0)
	v_mfma_f32_16x16x32_bf16 v[84:87], v[248:251], v[40:43], v[84:87]
	ds_read_b128 v[244:247], v209 offset:60992
	ds_read_b128 v[248:251], v216 offset:64
	s_waitcnt lgkmcnt(1)
	v_mfma_f32_16x16x32_bf16 v[244:247], v[244:247], v[40:43], v[20:23]
	s_waitcnt lgkmcnt(0)
	v_mfma_f32_16x16x32_bf16 v[248:251], v[248:251], v[40:43], v[24:27]
	s_nop 0
	ds_read_b128 v[20:23], v209 offset:65344
	s_nop 0
	ds_read_b128 v[24:27], v217 offset:64
	s_waitcnt lgkmcnt(1)
	v_mfma_f32_16x16x32_bf16 v[8:11], v[20:23], v[40:43], v[8:11]
	s_waitcnt lgkmcnt(0)
	v_mfma_f32_16x16x32_bf16 v[4:7], v[24:27], v[40:43], v[4:7]
	ds_read_b128 v[20:23], v209 offset:34944
	ds_read_b128 v[24:27], v210 offset:128
	s_waitcnt lgkmcnt(1)
	v_mfma_f32_16x16x32_bf16 v[40:43], v[20:23], v[28:31], v[12:15]
	s_waitcnt lgkmcnt(0)
	v_mfma_f32_16x16x32_bf16 v[130:133], v[24:27], v[28:31], v[16:19]
	s_nop 0
	ds_read_b128 v[12:15], v209 offset:39296
	s_nop 0
	ds_read_b128 v[16:19], v211 offset:128
	s_waitcnt lgkmcnt(1)
	v_mfma_f32_16x16x32_bf16 v[32:35], v[12:15], v[28:31], v[32:35]
	s_waitcnt lgkmcnt(0)
	v_mfma_f32_16x16x32_bf16 v[36:39], v[16:19], v[28:31], v[36:39]
	ds_read_b128 v[12:15], v209 offset:43648
	ds_read_b128 v[16:19], v212 offset:128
	s_waitcnt lgkmcnt(1)
	v_mfma_f32_16x16x32_bf16 v[44:47], v[12:15], v[28:31], v[44:47]
	s_waitcnt lgkmcnt(0)
	v_mfma_f32_16x16x32_bf16 v[88:91], v[16:19], v[28:31], v[88:91]
	ds_read_b128 v[12:15], v209 offset:48000
	ds_read_b128 v[16:19], v213 offset:128
	s_waitcnt lgkmcnt(1)
	v_mfma_f32_16x16x32_bf16 v[92:95], v[12:15], v[28:31], v[92:95]
	s_waitcnt lgkmcnt(0)
	v_mfma_f32_16x16x32_bf16 v[232:235], v[16:19], v[28:31], v[232:235]
	ds_read_b128 v[12:15], v209 offset:52352
	ds_read_b128 v[16:19], v214 offset:128
	s_waitcnt lgkmcnt(1)
	v_mfma_f32_16x16x32_bf16 v[236:239], v[12:15], v[28:31], v[236:239]
	s_waitcnt lgkmcnt(0)
	v_mfma_f32_16x16x32_bf16 v[240:243], v[16:19], v[28:31], v[240:243]
	ds_read_b128 v[12:15], v209 offset:56704
	ds_read_b128 v[16:19], v215 offset:128
	s_waitcnt lgkmcnt(1)
	v_mfma_f32_16x16x32_bf16 v[20:23], v[12:15], v[28:31], v[80:83]
	s_waitcnt lgkmcnt(0)
	v_mfma_f32_16x16x32_bf16 v[24:27], v[16:19], v[28:31], v[84:87]
	ds_read_b128 v[12:15], v209 offset:61056
	ds_read_b128 v[16:19], v216 offset:128
	ds_read_b128 v[80:83], v209 offset:65408
	ds_read_b128 v[84:87], v217 offset:128
	s_waitcnt lgkmcnt(3)
	v_mfma_f32_16x16x32_bf16 v[12:15], v[12:15], v[28:31], v[244:247]
	s_waitcnt lgkmcnt(2)
	v_mfma_f32_16x16x32_bf16 v[16:19], v[16:19], v[28:31], v[248:251]
	s_waitcnt lgkmcnt(1)
	v_mfma_f32_16x16x32_bf16 v[8:11], v[80:83], v[28:31], v[8:11]
	s_waitcnt lgkmcnt(0)
	v_mfma_f32_16x16x32_bf16 v[4:7], v[84:87], v[28:31], v[4:7]
	ds_read_b128 v[28:31], v209 offset:35008
	ds_read_b128 v[80:83], v210 offset:192
	s_waitcnt lgkmcnt(1)
	v_mfma_f32_16x16x32_bf16 v[28:31], v[28:31], v[0:3], v[40:43]
	s_waitcnt lgkmcnt(0)
	v_mfma_f32_16x16x32_bf16 v[40:43], v[80:83], v[0:3], v[130:133]
	ds_read_b128 v[80:83], v209 offset:39360
	ds_read_b128 v[84:87], v211 offset:192
	s_waitcnt lgkmcnt(1)
	v_mfma_f32_16x16x32_bf16 v[80:83], v[80:83], v[0:3], v[32:35]
	s_waitcnt lgkmcnt(0)
	v_mfma_f32_16x16x32_bf16 v[34:37], v[84:87], v[0:3], v[36:39]
	ds_read_b128 v[84:87], v209 offset:43712
	ds_read_b128 v[130:133], v212 offset:192
	s_waitcnt lgkmcnt(1)
	v_mfma_f32_16x16x32_bf16 v[44:47], v[84:87], v[0:3], v[44:47]
	s_waitcnt lgkmcnt(0)
	v_mfma_f32_16x16x32_bf16 v[84:87], v[130:133], v[0:3], v[88:91]
	s_nop 2
	ds_read_b128 v[88:91], v209 offset:48064
	ds_read_b128 v[130:133], v213 offset:192
	s_waitcnt lgkmcnt(1)
	v_mfma_f32_16x16x32_bf16 v[88:91], v[88:91], v[0:3], v[92:95]
	s_waitcnt lgkmcnt(0)
	v_mfma_f32_16x16x32_bf16 v[92:95], v[130:133], v[0:3], v[232:235]
	ds_read_b128 v[130:133], v209 offset:52416
	s_nop 1
	ds_read_b128 v[232:235], v214 offset:192
	s_waitcnt lgkmcnt(1)
	v_mfma_f32_16x16x32_bf16 v[130:133], v[130:133], v[0:3], v[236:239]
	s_waitcnt lgkmcnt(0)
	v_mfma_f32_16x16x32_bf16 v[232:235], v[232:235], v[0:3], v[240:243]
	s_nop 0
	ds_read_b128 v[236:239], v209 offset:56768
	s_nop 0
	ds_read_b128 v[240:243], v215 offset:192
	s_waitcnt lgkmcnt(1)
	v_mfma_f32_16x16x32_bf16 v[236:239], v[236:239], v[0:3], v[20:23]
	s_waitcnt lgkmcnt(0)
	v_mfma_f32_16x16x32_bf16 v[240:243], v[240:243], v[0:3], v[24:27]
	s_nop 0
	ds_read_b128 v[20:23], v209 offset:61120
	s_nop 0
	ds_read_b128 v[24:27], v216 offset:192
	s_waitcnt lgkmcnt(1)
; __device__ __forceinline__ float fexp2(float x) { return __builtin_amdgcn_exp2f(x); }
; #define MFMA16(a, b, c) __builtin_amdgcn_mfma_f32_16x16x32_bf16((a), (b), (c), 0, 0, 0)
; __device__ __forceinline__ void ret_unit(LAS unsigned char* lds, int u, const bf16* PROJ, const int* pos, const float* dec_f, const float* dec_b, const bf16* ST,
;                                          const float* gn_w, const float* gn_b, bf16* MIX, int tid, const WsRef& wsr) {
;     ...
;                 tf[n] = MFMA16(yf, qf[kk], tf[n]); tb[n] = MFMA16(yb, qf[kk], tb[n]); }
;         const float xif = fexp2(lgf2 * (float)(q + 1)), xib = fexp2(lgb2 * (float)(128 - q));
; #pragma unroll
;         for (int n = 0; n < 8; ++n) o[n] = o[n] + tf[n] * xif + tb[n] * xib;
;     }
;     float sm = 0.f;
; #pragma unroll
;     for (int n = 0; n < 8; ++n) sm += (o[n][0] + o[n][1]) + (o[n][2] + o[n][3]);
;     sm += __shfl_xor(sm, 16); sm += __shfl_xor(sm, 32);
	v_mfma_f32_16x16x32_bf16 v[12:15], v[20:23], v[0:3], v[12:15]
	s_waitcnt lgkmcnt(0)
	v_mfma_f32_16x16x32_bf16 v[244:247], v[24:27], v[0:3], v[16:19]
	s_nop 2
	ds_read_b128 v[16:19], v209 offset:65472
	ds_read_b128 v[20:23], v217 offset:192
	s_waitcnt lgkmcnt(1)
	v_mfma_f32_16x16x32_bf16 v[8:11], v[16:19], v[0:3], v[8:11]
	s_waitcnt lgkmcnt(0)
	v_mfma_f32_16x16x32_bf16 v[248:251], v[20:23], v[0:3], v[4:7]
	v_mul_f32_e32 v0, v105, v218
	v_exp_f32_e32 v38, v0
	v_mul_f32_e32 v0, v230, v219
	v_exp_f32_e32 v230, v0
	v_pk_fma_f32 v[2:3], v[38:39], v[28:29], v[52:53] op_sel_hi:[0,1,1]
	v_pk_fma_f32 v[16:17], v[38:39], v[132:133], v[70:71] op_sel_hi:[0,1,1]
	v_pk_fma_f32 v[0:1], v[38:39], v[30:31], v[54:55] op_sel_hi:[0,1,1]
	v_pk_fma_f32 v[32:33], v[230:231], v[40:41], v[2:3] op_sel_hi:[0,1,1]
	v_pk_fma_f32 v[2:3], v[38:39], v[80:81], v[56:57] op_sel_hi:[0,1,1]
	v_pk_fma_f32 v[18:19], v[38:39], v[130:131], v[68:69] op_sel_hi:[0,1,1]
	v_pk_fma_f32 v[22:23], v[230:231], v[234:235], v[16:17] op_sel_hi:[0,1,1]
	v_pk_fma_f32 v[16:17], v[38:39], v[238:239], v[74:75] op_sel_hi:[0,1,1]
	v_pk_fma_f32 v[12:13], v[38:39], v[12:13], v[76:77] op_sel_hi:[0,1,1]
	v_pk_fma_f32 v[30:31], v[230:231], v[42:43], v[0:1] op_sel_hi:[0,1,1]
	v_pk_fma_f32 v[0:1], v[38:39], v[82:83], v[58:59] op_sel_hi:[0,1,1]
	v_pk_fma_f32 v[28:29], v[230:231], v[34:35], v[2:3] op_sel_hi:[0,1,1]
	v_pk_fma_f32 v[24:25], v[230:231], v[232:233], v[18:19] op_sel_hi:[0,1,1]
	v_pk_fma_f32 v[18:19], v[230:231], v[242:243], v[16:17] op_sel_hi:[0,1,1]
	v_pk_fma_f32 v[16:17], v[230:231], v[244:245], v[12:13] op_sel_hi:[0,1,1]
	v_pk_fma_f32 v[10:11], v[38:39], v[10:11], v[50:51] op_sel_hi:[0,1,1]
	v_pk_fma_f32 v[12:13], v[38:39], v[8:9], v[48:49] op_sel_hi:[0,1,1]
	v_pk_fma_f32 v[26:27], v[230:231], v[36:37], v[0:1] op_sel_hi:[0,1,1]
	v_pk_fma_f32 v[8:9], v[230:231], v[250:251], v[10:11] op_sel_hi:[0,1,1]
	v_pk_fma_f32 v[10:11], v[230:231], v[248:249], v[12:13] op_sel_hi:[0,1,1]
	v_mov_b32_e32 v12, v32
	v_mov_b32_e32 v13, v28
	v_mov_b32_e32 v34, v33
	v_mov_b32_e32 v35, v29
	v_pk_fma_f32 v[0:1], v[38:39], v[46:47], v[62:63] op_sel_hi:[0,1,1]
	v_pk_fma_f32 v[2:3], v[38:39], v[44:45], v[60:61] op_sel_hi:[0,1,1]
	v_pk_add_f32 v[12:13], v[12:13], v[34:35]
	v_mov_b32_e32 v34, v30
	v_mov_b32_e32 v35, v26
	v_mov_b32_e32 v36, v31
	v_mov_b32_e32 v37, v27
	v_pk_fma_f32 v[4:5], v[230:231], v[86:87], v[0:1] op_sel_hi:[0,1,1]
	v_pk_fma_f32 v[6:7], v[230:231], v[84:85], v[2:3] op_sel_hi:[0,1,1]
	v_pk_add_f32 v[34:35], v[34:35], v[36:37]
	v_mov_b32_e32 v36, v6
	v_pk_add_f32 v[12:13], v[12:13], v[34:35]
	v_pk_mov_b32 v[34:35], v[6:7], v[4:5] op_sel:[1,0]
	v_mov_b32_e32 v37, v5
	v_pk_fma_f32 v[0:1], v[38:39], v[90:91], v[66:67] op_sel_hi:[0,1,1]
	v_pk_fma_f32 v[2:3], v[38:39], v[88:89], v[64:65] op_sel_hi:[0,1,1]
	v_pk_add_f32 v[34:35], v[34:35], v[36:37]
	v_pk_fma_f32 v[0:1], v[230:231], v[94:95], v[0:1] op_sel_hi:[0,1,1]
	v_pk_fma_f32 v[2:3], v[230:231], v[92:93], v[2:3] op_sel_hi:[0,1,1]
	v_add_f32_e32 v12, 0, v12
	v_pk_add_f32 v[34:35], v[34:35], v[34:35] op_sel:[0,1] op_sel_hi:[1,0]
	v_pk_fma_f32 v[20:21], v[38:39], v[236:237], v[72:73] op_sel_hi:[0,1,1]
	v_pk_fma_f32 v[14:15], v[38:39], v[14:15], v[78:79] op_sel_hi:[0,1,1]
	v_add_f32_e32 v12, v12, v13
	v_add_f32_e32 v36, v2, v3
	v_add_f32_e32 v38, v0, v1
	v_mov_b32_e32 v13, v24
	v_mov_b32_e32 v35, v25
	v_mov_b32_e32 v37, v22
	v_mov_b32_e32 v39, v23
	v_pk_fma_f32 v[20:21], v[230:231], v[240:241], v[20:21] op_sel_hi:[0,1,1]
	v_pk_add_f32 v[12:13], v[12:13], v[34:35]
	v_pk_add_f32 v[34:35], v[36:37], v[38:39]
	v_mov_b32_e32 v36, v20
	v_pk_add_f32 v[12:13], v[12:13], v[34:35]
	v_pk_mov_b32 v[34:35], v[20:21], v[18:19] op_sel:[1,0]
	v_mov_b32_e32 v37, v19
	v_pk_add_f32 v[34:35], v[34:35], v[36:37]
	v_pk_fma_f32 v[14:15], v[230:231], v[246:247], v[14:15] op_sel_hi:[0,1,1]
	v_pk_add_f32 v[12:13], v[12:13], v[12:13] op_sel:[0,1] op_sel_hi:[1,0]
	v_pk_add_f32 v[34:35], v[34:35], v[34:35] op_sel:[0,1] op_sel_hi:[1,0]
	v_add_f32_e32 v36, v16, v17
	v_add_f32_e32 v38, v14, v15
	v_mov_b32_e32 v13, v10
	v_mov_b32_e32 v35, v11
	v_mov_b32_e32 v37, v8
	v_mov_b32_e32 v39, v9
	v_pk_add_f32 v[12:13], v[12:13], v[34:35]
	v_pk_add_f32 v[34:35], v[36:37], v[38:39]
	v_or_b32_e32 v48, s0, v126
	v_pk_add_f32 v[12:13], v[12:13], v[34:35]
	v_mov_b32_e32 v49, v97
	v_add_f32_e32 v12, v12, v13
	ds_bpermute_b32 v13, v220, v12
	s_waitcnt lgkmcnt(0)
	v_add_f32_e32 v12, v12, v13
	ds_bpermute_b32 v13, v221, v12
	s_waitcnt lgkmcnt(0)
; __device__ __forceinline__ void ret_unit(LAS unsigned char* lds, int u, const bf16* PROJ, const int* pos, const float* dec_f, const float* dec_b, const bf16* ST,
;                                          const float* gn_w, const float* gn_b, bf16* MIX, int tid, const WsRef& wsr) {
;     ...
;     const float mu = sm * (1.f / 128.f);
;     float vq = 0.f;
; #pragma unroll
;     for (int n = 0; n < 8; ++n) { const f32x4 d = o[n] - mu; vq += (d[0] * d[0] + d[1] * d[1]) + (d[2] * d[2] + d[3] * d[3]); }
;     vq += __shfl_xor(vq, 16); vq += __shfl_xor(vq, 32);
;     const float rstd = rsqrtf(vq * (1.f / 128.f) + EPS);
;     const size_t row = row0 + q;
; #pragma unroll
;     for (int n = 0; n < 8; ++n) { const int col = h * 128 + n * 16 + 4 * fq;
;         const f32x4 gw = *(const f32x4*)(gn_w + col), gb = *(const f32x4*)(gn_b + col);
;         const u32x2 gg = *(const u32x2*)(PROJ + row * INC + 1536 + col);
	v_add_f32_e32 v40, v12, v13
	v_fmamk_f32 v33, v40, 0xbc000000, v33
	v_fmamk_f32 v29, v40, 0xbc000000, v29
	v_fmamk_f32 v31, v40, 0xbc000000, v31
	v_fmac_f32_e32 v32, 0xbc000000, v40
	v_fmamk_f32 v27, v40, 0xbc000000, v27
	v_fmac_f32_e32 v28, 0xbc000000, v40
	v_mov_b32_e32 v34, v33
	v_mov_b32_e32 v35, v29
	v_fmac_f32_e32 v30, 0xbc000000, v40
	v_fmac_f32_e32 v26, 0xbc000000, v40
	v_mov_b32_e32 v12, v32
	v_mov_b32_e32 v13, v28
	v_pk_mul_f32 v[34:35], v[34:35], v[34:35]
	v_mov_b32_e32 v36, v31
	v_mov_b32_e32 v37, v27
	v_pk_fma_f32 v[12:13], v[12:13], v[12:13], v[34:35]
	v_mov_b32_e32 v34, v30
	v_mov_b32_e32 v35, v26
	v_pk_mul_f32 v[36:37], v[36:37], v[36:37]
	v_fmamk_f32 v7, v40, 0xbc000000, v7
	v_pk_fma_f32 v[34:35], v[34:35], v[34:35], v[36:37]
	v_fmac_f32_e32 v6, 0xbc000000, v40
	v_pk_add_f32 v[12:13], v[12:13], v[34:35]
	v_fmamk_f32 v5, v40, 0xbc000000, v5
	v_fmac_f32_e32 v4, 0xbc000000, v40
	v_pk_add_f32 v[12:13], v[12:13], v[12:13] op_sel_hi:[0,1]
	v_pk_mul_f32 v[34:35], v[4:5], v[4:5]
	v_pk_mul_f32 v[36:37], v[6:7], v[6:7]
	v_fmac_f32_e32 v2, 0xbc000000, v40
	v_pk_mov_b32 v[38:39], v[36:37], v[34:35] op_sel:[1,0]
	v_mov_b32_e32 v37, v35
	v_fmamk_f32 v3, v40, 0xbc000000, v3
	v_fmac_f32_e32 v0, 0xbc000000, v40
	v_mul_f32_e32 v12, v2, v2
	v_pk_add_f32 v[34:35], v[38:39], v[36:37]
	v_fmamk_f32 v1, v40, 0xbc000000, v1
	v_pk_fma_f32 v[36:37], v[2:3], v[2:3], v[12:13] op_sel_hi:[1,1,0]
	v_mul_f32_e32 v12, v0, v0
	v_pk_add_f32 v[34:35], v[34:35], v[34:35] op_sel_hi:[0,1]
	v_pk_fma_f32 v[38:39], v[0:1], v[0:1], v[12:13] op_sel_hi:[1,1,0]
	v_fmamk_f32 v23, v40, 0xbc000000, v23
	v_fmac_f32_e32 v22, 0xbc000000, v40
	v_fmamk_f32 v25, v40, 0xbc000000, v25
	v_fmac_f32_e32 v24, 0xbc000000, v40
	v_mul_f32_e32 v36, v24, v24
	v_mul_f32_e32 v38, v25, v25
	v_mul_f32_e32 v34, v22, v22
	v_mul_f32_e32 v12, v23, v23
	v_pk_add_f32 v[36:37], v[36:37], v[38:39]
	v_pk_add_f32 v[12:13], v[34:35], v[12:13]
	v_fmamk_f32 v21, v40, 0xbc000000, v21
	v_pk_add_f32 v[12:13], v[36:37], v[12:13]
	v_fmac_f32_e32 v20, 0xbc000000, v40
	v_fmamk_f32 v19, v40, 0xbc000000, v19
	v_fmac_f32_e32 v18, 0xbc000000, v40
	v_pk_add_f32 v[12:13], v[12:13], v[12:13] op_sel_hi:[0,1]
	v_pk_mul_f32 v[34:35], v[18:19], v[18:19]
	v_pk_mul_f32 v[36:37], v[20:21], v[20:21]
	v_fmac_f32_e32 v16, 0xbc000000, v40
	v_pk_mov_b32 v[38:39], v[36:37], v[34:35] op_sel:[1,0]
	v_mov_b32_e32 v37, v35
	v_fmamk_f32 v17, v40, 0xbc000000, v17
	v_fmac_f32_e32 v14, 0xbc000000, v40
	v_mul_f32_e32 v12, v16, v16
	v_pk_add_f32 v[34:35], v[38:39], v[36:37]
	v_fmamk_f32 v15, v40, 0xbc000000, v15
	v_pk_fma_f32 v[36:37], v[16:17], v[16:17], v[12:13] op_sel_hi:[1,1,0]
	v_mul_f32_e32 v12, v14, v14
	v_pk_add_f32 v[34:35], v[34:35], v[34:35] op_sel_hi:[0,1]
	v_pk_fma_f32 v[38:39], v[14:15], v[14:15], v[12:13] op_sel_hi:[1,1,0]
	v_fmamk_f32 v9, v40, 0xbc000000, v9
	v_fmac_f32_e32 v8, 0xbc000000, v40
	v_fmamk_f32 v11, v40, 0xbc000000, v11
	v_fmac_f32_e32 v10, 0xbc000000, v40
	v_mul_f32_e32 v36, v10, v10
	v_mul_f32_e32 v38, v11, v11
	v_mul_f32_e32 v34, v8, v8
	v_mul_f32_e32 v12, v9, v9
	v_pk_add_f32 v[36:37], v[36:37], v[38:39]
	v_pk_add_f32 v[12:13], v[34:35], v[12:13]
	v_lshl_add_u64 v[34:35], s[4:5], 0, v[102:103]
	v_pk_add_f32 v[12:13], v[36:37], v[12:13]
	v_mov_b64_e32 v[36:37], s[6:7]
	v_add_f32_e32 v12, v12, v13
	ds_bpermute_b32 v13, v220, v12
	s_waitcnt lgkmcnt(0)
	v_add_f32_e32 v12, v12, v13
	ds_bpermute_b32 v13, v221, v12
	s_waitcnt lgkmcnt(0)
	v_add_f32_e32 v12, v12, v13
	v_fmamk_f32 v12, v12, 0x3c000000, v227
	v_cmp_gt_f32_e64 s[68:69], s1, v12
	v_mul_f32_e32 v13, 0x4b800000, v12
	v_mad_u64_u32 v[44:45], s[0:1], v34, s72, v[36:37]
	v_cndmask_b32_e64 v12, v12, v13, s[68:69]
	v_rsq_f32_e32 v12, v12
	v_mad_i32_i24 v45, v35, s72, v45
	v_lshlrev_b64 v[34:35], 11, v[34:35]
	v_lshl_add_u64 v[46:47], s[70:71], 0, v[34:35]
	v_mul_f32_e32 v13, 0x45800000, v12
	v_cndmask_b32_e64 v12, v12, v13, s[68:69]
	v_lshlrev_b32_e32 v13, 2, v48
	v_lshlrev_b32_e32 v48, 1, v48
	v_lshl_add_u64 v[34:35], v[44:45], 0, v[48:49]
	v_lshl_add_u64 v[46:47], v[46:47], 0, v[48:49]
	v_mbcnt_lo_u32_b32 v130, -1, 0
	v_mbcnt_hi_u32_b32 v130, -1, v130
	v_and_b32_e32 v130, 16, v130
	v_lshrrev_b32_e32 v131, 1, v130
	v_add_u32_e32 v130, v130, v131
	v_mov_b32_e32 v131, 0
	v_lshl_add_u64 v[46:47], v[46:47], 0, v[130:131]
	global_load_dwordx2 v[56:57], v[34:35], off offset:3072
	global_load_dwordx2 v[58:59], v[34:35], off offset:3104
	global_load_dwordx2 v[60:61], v[34:35], off offset:3136
	global_load_dwordx2 v[62:63], v[34:35], off offset:3168
	global_load_dwordx2 v[64:65], v[34:35], off offset:3200
	global_load_dwordx2 v[66:67], v[34:35], off offset:3232
	global_load_dwordx2 v[68:69], v[34:35], off offset:3264
	global_load_dwordx2 v[70:71], v[34:35], off offset:3296
	global_load_dwordx4 v[72:75], v13, s[22:23]
	global_load_dwordx4 v[76:79], v13, s[36:37]
	global_load_dwordx4 v[80:83], v13, s[22:23] offset:64
	global_load_dwordx4 v[84:87], v13, s[36:37] offset:64
	global_load_dwordx4 v[88:91], v13, s[22:23] offset:128
	global_load_dwordx4 v[92:95], v13, s[36:37] offset:128
	global_load_dwordx4 v[36:39], v13, s[22:23] offset:192
	global_load_dwordx4 v[40:43], v13, s[36:37] offset:192
	global_load_dwordx4 v[232:235], v13, s[22:23] offset:256
	global_load_dwordx4 v[236:239], v13, s[36:37] offset:256
	global_load_dwordx4 v[240:243], v13, s[22:23] offset:320
	global_load_dwordx4 v[248:251], v13, s[36:37] offset:320
	v_pk_mul_f32 v[32:33], v[32:33], v[12:13] op_sel_hi:[1,0]
	v_pk_mul_f32 v[30:31], v[30:31], v[12:13] op_sel_hi:[1,0]
	v_pk_mul_f32 v[28:29], v[28:29], v[12:13] op_sel_hi:[1,0]
	v_pk_mul_f32 v[26:27], v[26:27], v[12:13] op_sel_hi:[1,0]
	v_pk_mul_f32 v[6:7], v[6:7], v[12:13] op_sel_hi:[1,0]
	v_pk_mul_f32 v[4:5], v[4:5], v[12:13] op_sel_hi:[1,0]
	v_pk_mul_f32 v[2:3], v[2:3], v[12:13] op_sel_hi:[1,0]
	v_pk_mul_f32 v[0:1], v[0:1], v[12:13] op_sel_hi:[1,0]
	v_pk_mul_f32 v[24:25], v[24:25], v[12:13] op_sel_hi:[1,0]
	v_pk_mul_f32 v[22:23], v[22:23], v[12:13] op_sel_hi:[1,0]
	v_pk_mul_f32 v[20:21], v[20:21], v[12:13] op_sel_hi:[1,0]
	v_pk_mul_f32 v[18:19], v[18:19], v[12:13] op_sel_hi:[1,0]
	v_pk_mul_f32 v[16:17], v[16:17], v[12:13] op_sel_hi:[1,0]
	v_pk_mul_f32 v[14:15], v[14:15], v[12:13] op_sel_hi:[1,0]
	v_pk_mul_f32 v[10:11], v[10:11], v[12:13] op_sel_hi:[1,0]
	v_pk_mul_f32 v[8:9], v[8:9], v[12:13] op_sel_hi:[1,0]
	s_waitcnt vmcnt(10)
; __device__ __forceinline__ unsigned pk2(float lo, float hi) { return pg8::cvt_pk_bf16(lo, hi); }
; __device__ __forceinline__ float bflo(unsigned w) { return __uint_as_float(w << 16); }
; __device__ __forceinline__ float bfhi(unsigned w) { return __uint_as_float(w & 0xffff0000u); }
; __device__ __forceinline__ void ret_unit(LAS unsigned char* lds, int u, const bf16* PROJ, const int* pos, const float* dec_f, const float* dec_b, const bf16* ST,
;                                          const float* gn_w, const float* gn_b, bf16* MIX, int tid, const WsRef& wsr) {
;     ...
;     for (int n = 0; n < 8; ++n) { const int col = h * 128 + n * 16 + 4 * fq;
;         const f32x4 gw = *(const f32x4*)(gn_w + col), gb = *(const f32x4*)(gn_b + col);
;         const u32x2 gg = *(const u32x2*)(PROJ + row * INC + 1536 + col);
;         const f32x4 g = (f32x4){bflo(gg.x), bfhi(gg.x), bflo(gg.y), bfhi(gg.y)};
;         f32x4 y = (o[n] - mu) * rstd * gw + gb;
; #pragma unroll
;         for (int r = 0; r < 4; ++r) y[r] = y[r] * g[r] * __builtin_amdgcn_rcpf(1.f + __expf(-g[r]));
;         u32x2 w; w.x = pk2(y[0], y[1]); w.y = pk2(y[2], y[3]); *(u32x2*)(MIX + row * D + col) = w; }
	v_lshlrev_b32_e32 v130, 16, v56
	v_and_b32_e32 v131, 0xffff0000, v56
	v_lshlrev_b32_e32 v132, 16, v57
	v_and_b32_e32 v133, 0xffff0000, v57
	v_pk_fma_f32 v[32:33], v[72:73], v[32:33], v[76:77]
	v_pk_fma_f32 v[30:31], v[74:75], v[30:31], v[78:79]
	global_load_dwordx4 v[72:75], v13, s[22:23] offset:384
	global_load_dwordx4 v[76:79], v13, s[36:37] offset:384
	v_mul_f32_e32 v56, 0xbfb8aa3b, v130
	v_mul_f32_e32 v57, 0xbfb8aa3b, v131
	v_exp_f32_e32 v56, v56
	v_exp_f32_e32 v57, v57
	v_pk_mul_f32 v[32:33], v[32:33], v[130:131]
	v_mul_f32_e32 v130, 0xbfb8aa3b, v132
	v_mul_f32_e32 v131, 0xbfb8aa3b, v133
	v_add_f32_e32 v56, 1.0, v56
	v_add_f32_e32 v57, 1.0, v57
	v_rcp_f32_e32 v56, v56
	v_rcp_f32_e32 v57, v57
	v_exp_f32_e32 v130, v130
	v_exp_f32_e32 v131, v131
	v_pk_mul_f32 v[30:31], v[30:31], v[132:133]
	v_pk_mul_f32 v[32:33], v[56:57], v[32:33]
	v_add_f32_e32 v130, 1.0, v130
	v_add_f32_e32 v131, 1.0, v131
	v_rcp_f32_e32 v130, v130
	v_rcp_f32_e32 v131, v131
	v_cvt_pk_bf16_f32 v56, v32, v33
	s_nop 0
	v_pk_mul_f32 v[30:31], v[130:131], v[30:31]
	s_nop 0
	v_cvt_pk_bf16_f32 v57, v30, v31
	s_waitcnt vmcnt(10)
	v_lshlrev_b32_e32 v130, 16, v58
	v_and_b32_e32 v131, 0xffff0000, v58
	v_lshlrev_b32_e32 v132, 16, v59
	v_and_b32_e32 v133, 0xffff0000, v59
	v_pk_fma_f32 v[28:29], v[80:81], v[28:29], v[84:85]
	v_pk_fma_f32 v[26:27], v[82:83], v[26:27], v[86:87]
	global_load_dwordx4 v[80:83], v13, s[22:23] offset:448
	global_load_dwordx4 v[84:87], v13, s[36:37] offset:448
	v_mul_f32_e32 v58, 0xbfb8aa3b, v130
	v_mul_f32_e32 v59, 0xbfb8aa3b, v131
	v_exp_f32_e32 v58, v58
	v_exp_f32_e32 v59, v59
	v_pk_mul_f32 v[28:29], v[28:29], v[130:131]
	v_mul_f32_e32 v130, 0xbfb8aa3b, v132
	v_mul_f32_e32 v131, 0xbfb8aa3b, v133
	v_add_f32_e32 v58, 1.0, v58
	v_add_f32_e32 v59, 1.0, v59
	v_rcp_f32_e32 v58, v58
	v_rcp_f32_e32 v59, v59
	v_exp_f32_e32 v130, v130
	v_exp_f32_e32 v131, v131
	v_pk_mul_f32 v[26:27], v[26:27], v[132:133]
	v_pk_mul_f32 v[28:29], v[58:59], v[28:29]
	v_add_f32_e32 v130, 1.0, v130
	v_add_f32_e32 v131, 1.0, v131
	v_rcp_f32_e32 v130, v130
	v_rcp_f32_e32 v131, v131
	v_cvt_pk_bf16_f32 v58, v28, v29
	s_nop 0
	v_pk_mul_f32 v[26:27], v[130:131], v[26:27]
	s_nop 0
	v_cvt_pk_bf16_f32 v59, v26, v27
	s_nop 1
	v_permlane16_swap_b32_e32 v56, v58
	v_permlane16_swap_b32_e32 v57, v59
	global_store_dwordx4 v[46:47], v[56:59], off sc1
	s_waitcnt vmcnt(11)
	v_lshlrev_b32_e32 v130, 16, v60
	v_and_b32_e32 v131, 0xffff0000, v60
	v_lshlrev_b32_e32 v132, 16, v61
	v_and_b32_e32 v133, 0xffff0000, v61
	v_pk_fma_f32 v[6:7], v[88:89], v[6:7], v[92:93]
	v_pk_fma_f32 v[4:5], v[90:91], v[4:5], v[94:95]
	v_mul_f32_e32 v60, 0xbfb8aa3b, v130
	v_mul_f32_e32 v61, 0xbfb8aa3b, v131
	v_exp_f32_e32 v60, v60
	v_exp_f32_e32 v61, v61
	v_pk_mul_f32 v[6:7], v[6:7], v[130:131]
	v_mul_f32_e32 v130, 0xbfb8aa3b, v132
	v_mul_f32_e32 v131, 0xbfb8aa3b, v133
	v_add_f32_e32 v60, 1.0, v60
	v_add_f32_e32 v61, 1.0, v61
	v_rcp_f32_e32 v60, v60
	v_rcp_f32_e32 v61, v61
	v_exp_f32_e32 v130, v130
	v_exp_f32_e32 v131, v131
	v_pk_mul_f32 v[4:5], v[4:5], v[132:133]
	v_pk_mul_f32 v[6:7], v[60:61], v[6:7]
	v_add_f32_e32 v130, 1.0, v130
	v_add_f32_e32 v131, 1.0, v131
	v_rcp_f32_e32 v130, v130
	v_rcp_f32_e32 v131, v131
	v_cvt_pk_bf16_f32 v60, v6, v7
	s_nop 0
	v_pk_mul_f32 v[4:5], v[130:131], v[4:5]
	s_nop 0
	v_cvt_pk_bf16_f32 v61, v4, v5
	s_waitcnt vmcnt(9)
	v_lshlrev_b32_e32 v130, 16, v62
	v_and_b32_e32 v131, 0xffff0000, v62
	v_lshlrev_b32_e32 v132, 16, v63
	v_and_b32_e32 v133, 0xffff0000, v63
	v_pk_fma_f32 v[2:3], v[36:37], v[2:3], v[40:41]
	v_pk_fma_f32 v[0:1], v[38:39], v[0:1], v[42:43]
	v_mul_f32_e32 v62, 0xbfb8aa3b, v130
	v_mul_f32_e32 v63, 0xbfb8aa3b, v131
	v_exp_f32_e32 v62, v62
	v_exp_f32_e32 v63, v63
	v_pk_mul_f32 v[2:3], v[2:3], v[130:131]
	v_mul_f32_e32 v130, 0xbfb8aa3b, v132
	v_mul_f32_e32 v131, 0xbfb8aa3b, v133
	v_add_f32_e32 v62, 1.0, v62
	v_add_f32_e32 v63, 1.0, v63
	v_rcp_f32_e32 v62, v62
	v_rcp_f32_e32 v63, v63
	v_exp_f32_e32 v130, v130
	v_exp_f32_e32 v131, v131
	v_pk_mul_f32 v[0:1], v[0:1], v[132:133]
	v_pk_mul_f32 v[2:3], v[62:63], v[2:3]
	v_add_f32_e32 v130, 1.0, v130
	v_add_f32_e32 v131, 1.0, v131
	v_rcp_f32_e32 v130, v130
	v_rcp_f32_e32 v131, v131
	v_cvt_pk_bf16_f32 v62, v2, v3
	s_nop 0
	v_pk_mul_f32 v[0:1], v[130:131], v[0:1]
	s_nop 0
	v_cvt_pk_bf16_f32 v63, v0, v1
	s_nop 1
	v_permlane16_swap_b32_e32 v60, v62
	v_permlane16_swap_b32_e32 v61, v63
	global_store_dwordx4 v[46:47], v[60:63], off offset:64 sc1
	s_waitcnt vmcnt(8)
; __device__ __forceinline__ unsigned pk2(float lo, float hi) { return pg8::cvt_pk_bf16(lo, hi); }
; __device__ __forceinline__ float bflo(unsigned w) { return __uint_as_float(w << 16); }
; __device__ __forceinline__ float bfhi(unsigned w) { return __uint_as_float(w & 0xffff0000u); }
; __device__ __forceinline__ void ret_unit(LAS unsigned char* lds, int u, const bf16* PROJ, const int* pos, const float* dec_f, const float* dec_b, const bf16* ST,
;                                          const float* gn_w, const float* gn_b, bf16* MIX, int tid, const WsRef& wsr) {
;     ...
;     for (int n = 0; n < 8; ++n) { const int col = h * 128 + n * 16 + 4 * fq;
;         const f32x4 gw = *(const f32x4*)(gn_w + col), gb = *(const f32x4*)(gn_b + col);
;         const u32x2 gg = *(const u32x2*)(PROJ + row * INC + 1536 + col);
;         const f32x4 g = (f32x4){bflo(gg.x), bfhi(gg.x), bflo(gg.y), bfhi(gg.y)};
;         f32x4 y = (o[n] - mu) * rstd * gw + gb;
; #pragma unroll
;         for (int r = 0; r < 4; ++r) y[r] = y[r] * g[r] * __builtin_amdgcn_rcpf(1.f + __expf(-g[r]));
;         u32x2 w; w.x = pk2(y[0], y[1]); w.y = pk2(y[2], y[3]); *(u32x2*)(MIX + row * D + col) = w; }
;     __syncthreads();
	v_lshlrev_b32_e32 v130, 16, v64
	v_and_b32_e32 v131, 0xffff0000, v64
	v_lshlrev_b32_e32 v132, 16, v65
	v_and_b32_e32 v133, 0xffff0000, v65
	v_pk_fma_f32 v[24:25], v[232:233], v[24:25], v[236:237]
	v_pk_fma_f32 v[22:23], v[234:235], v[22:23], v[238:239]
	v_mul_f32_e32 v64, 0xbfb8aa3b, v130
	v_mul_f32_e32 v65, 0xbfb8aa3b, v131
	v_exp_f32_e32 v64, v64
	v_exp_f32_e32 v65, v65
	v_pk_mul_f32 v[24:25], v[24:25], v[130:131]
	v_mul_f32_e32 v130, 0xbfb8aa3b, v132
	v_mul_f32_e32 v131, 0xbfb8aa3b, v133
	v_add_f32_e32 v64, 1.0, v64
	v_add_f32_e32 v65, 1.0, v65
	v_rcp_f32_e32 v64, v64
	v_rcp_f32_e32 v65, v65
	v_exp_f32_e32 v130, v130
	v_exp_f32_e32 v131, v131
	v_pk_mul_f32 v[22:23], v[22:23], v[132:133]
	v_pk_mul_f32 v[24:25], v[64:65], v[24:25]
	v_add_f32_e32 v130, 1.0, v130
	v_add_f32_e32 v131, 1.0, v131
	v_rcp_f32_e32 v130, v130
	v_rcp_f32_e32 v131, v131
	v_cvt_pk_bf16_f32 v64, v24, v25
	s_nop 0
	v_pk_mul_f32 v[22:23], v[130:131], v[22:23]
	s_nop 0
	v_cvt_pk_bf16_f32 v65, v22, v23
	s_waitcnt vmcnt(6)
	v_lshlrev_b32_e32 v130, 16, v66
	v_and_b32_e32 v131, 0xffff0000, v66
	v_lshlrev_b32_e32 v132, 16, v67
	v_and_b32_e32 v133, 0xffff0000, v67
	v_pk_fma_f32 v[20:21], v[240:241], v[20:21], v[248:249]
	v_pk_fma_f32 v[18:19], v[242:243], v[18:19], v[250:251]
	v_mul_f32_e32 v66, 0xbfb8aa3b, v130
	v_mul_f32_e32 v67, 0xbfb8aa3b, v131
	v_exp_f32_e32 v66, v66
	v_exp_f32_e32 v67, v67
	v_pk_mul_f32 v[20:21], v[20:21], v[130:131]
	v_mul_f32_e32 v130, 0xbfb8aa3b, v132
	v_mul_f32_e32 v131, 0xbfb8aa3b, v133
	v_add_f32_e32 v66, 1.0, v66
	v_add_f32_e32 v67, 1.0, v67
	v_rcp_f32_e32 v66, v66
	v_rcp_f32_e32 v67, v67
	v_exp_f32_e32 v130, v130
	v_exp_f32_e32 v131, v131
	v_pk_mul_f32 v[18:19], v[18:19], v[132:133]
	v_pk_mul_f32 v[20:21], v[66:67], v[20:21]
	v_add_f32_e32 v130, 1.0, v130
	v_add_f32_e32 v131, 1.0, v131
	v_rcp_f32_e32 v130, v130
	v_rcp_f32_e32 v131, v131
	v_cvt_pk_bf16_f32 v66, v20, v21
	s_nop 0
	v_pk_mul_f32 v[18:19], v[130:131], v[18:19]
	s_nop 0
	v_cvt_pk_bf16_f32 v67, v18, v19
	s_nop 1
	v_permlane16_swap_b32_e32 v64, v66
	v_permlane16_swap_b32_e32 v65, v67
	global_store_dwordx4 v[46:47], v[64:67], off offset:128 sc1
	s_waitcnt vmcnt(5)
	v_lshlrev_b32_e32 v130, 16, v68
	v_and_b32_e32 v131, 0xffff0000, v68
	v_lshlrev_b32_e32 v132, 16, v69
	v_and_b32_e32 v133, 0xffff0000, v69
	v_pk_fma_f32 v[16:17], v[72:73], v[16:17], v[76:77]
	v_pk_fma_f32 v[14:15], v[74:75], v[14:15], v[78:79]
	v_mul_f32_e32 v68, 0xbfb8aa3b, v130
	v_mul_f32_e32 v69, 0xbfb8aa3b, v131
	v_exp_f32_e32 v68, v68
	v_exp_f32_e32 v69, v69
	v_pk_mul_f32 v[16:17], v[16:17], v[130:131]
	v_mul_f32_e32 v130, 0xbfb8aa3b, v132
	v_mul_f32_e32 v131, 0xbfb8aa3b, v133
	v_add_f32_e32 v68, 1.0, v68
	v_add_f32_e32 v69, 1.0, v69
	v_rcp_f32_e32 v68, v68
	v_rcp_f32_e32 v69, v69
	v_exp_f32_e32 v130, v130
	v_exp_f32_e32 v131, v131
	v_pk_mul_f32 v[14:15], v[14:15], v[132:133]
	v_pk_mul_f32 v[16:17], v[68:69], v[16:17]
	v_add_f32_e32 v130, 1.0, v130
	v_add_f32_e32 v131, 1.0, v131
	v_rcp_f32_e32 v130, v130
	v_rcp_f32_e32 v131, v131
	v_cvt_pk_bf16_f32 v68, v16, v17
	s_nop 0
	v_pk_mul_f32 v[14:15], v[130:131], v[14:15]
	s_nop 0
	v_cvt_pk_bf16_f32 v69, v14, v15
	s_waitcnt vmcnt(3)
	v_lshlrev_b32_e32 v130, 16, v70
	v_and_b32_e32 v131, 0xffff0000, v70
	v_lshlrev_b32_e32 v132, 16, v71
	v_and_b32_e32 v133, 0xffff0000, v71
	v_pk_fma_f32 v[10:11], v[80:81], v[10:11], v[84:85]
	v_pk_fma_f32 v[8:9], v[82:83], v[8:9], v[86:87]
	v_mul_f32_e32 v70, 0xbfb8aa3b, v130
	v_mul_f32_e32 v71, 0xbfb8aa3b, v131
	v_exp_f32_e32 v70, v70
	v_exp_f32_e32 v71, v71
	v_pk_mul_f32 v[10:11], v[10:11], v[130:131]
	v_mul_f32_e32 v130, 0xbfb8aa3b, v132
	v_mul_f32_e32 v131, 0xbfb8aa3b, v133
	v_add_f32_e32 v70, 1.0, v70
	v_add_f32_e32 v71, 1.0, v71
	v_rcp_f32_e32 v70, v70
	v_rcp_f32_e32 v71, v71
	v_exp_f32_e32 v130, v130
	v_exp_f32_e32 v131, v131
	v_pk_mul_f32 v[8:9], v[8:9], v[132:133]
	v_pk_mul_f32 v[10:11], v[70:71], v[10:11]
	v_add_f32_e32 v130, 1.0, v130
	v_add_f32_e32 v131, 1.0, v131
	v_rcp_f32_e32 v130, v130
	v_rcp_f32_e32 v131, v131
	v_cvt_pk_bf16_f32 v70, v10, v11
	s_nop 0
	v_pk_mul_f32 v[8:9], v[130:131], v[8:9]
	s_nop 0
	v_cvt_pk_bf16_f32 v71, v8, v9
	s_nop 1
	v_permlane16_swap_b32_e32 v68, v70
	v_permlane16_swap_b32_e32 v69, v71
	global_store_dwordx4 v[46:47], v[68:71], off offset:192 sc1
	s_barrier
	s_cbranch_scc1 .LBB0_438
	v_readlane_b32 s82, v255, 40
	v_readlane_b32 s4, v255, 38
	v_readlane_b32 s80, v255, 42
	v_readlane_b32 s83, v255, 41
	v_readlane_b32 s5, v255, 39
	v_readlane_b32 s2, v255, 58
	v_readlane_b32 s81, v255, 43
